# K-loop load segments issue their LDS-DMA group before the ds_read burst (more latency slack for the tile loads), counts and barriers unchanged
# baseline (speedup 1.0000x reference)
.Lc0s_first:
	s_add_i32 s62, s58, 0xfff80080
	s_and_b64 s[10:11], s[10:11], exec
	s_cselect_b32 s78, s54, s62
	s_cselect_b32 s62, s55, s60
	s_add_i32 s10, 0, 0x10000
	v_add_u32_e32 v0, s10, v157
	v_add_u32_e32 v147, s10, v158
	s_add_i32 s10, 0, 0x14000
	s_mov_b32 m0, s41
	s_nop 0
	buffer_load_dwordx4 v153, s[48:51], s58 offen lds
	s_mov_b32 m0, s42
	s_nop 0
	buffer_load_dwordx4 v155, s[48:51], s58 offen lds
	ds_read_b128 v[164:167], v0
	ds_read_b128 v[168:171], v0 offset:2048
	ds_read_b128 v[172:175], v147
	ds_read_b128 v[176:179], v147 offset:2048
	v_add_u32_e32 v0, s10, v157
	v_add_u32_e32 v147, s10, v158
	ds_read_b128 v[180:183], v0
	ds_read_b128 v[184:187], v0 offset:2048
	ds_read_b128 v[188:191], v147
	ds_read_b128 v[192:195], v147 offset:2048
	s_or_b32 s64, s78, 0x80
	s_or_b32 s65, s62, 0x80
	ds_read_b128 v[196:199], v161
	ds_read_b128 v[204:207], v161 offset:2048
	ds_read_b128 v[208:211], v162
	ds_read_b128 v[212:215], v162 offset:2048
	ds_read_b128 v[216:219], v161 offset:4096
	ds_read_b128 v[220:223], v161 offset:6144
	ds_read_b128 v[224:227], v162 offset:4096
	ds_read_b128 v[228:231], v162 offset:6144
	s_waitcnt vmcnt(8)
	s_waitcnt lgkmcnt(0)
	s_barrier
	s_waitcnt lgkmcnt(0)
	v_mfma_f32_16x16x32_f16 v[118:121], v[164:167], v[196:199], 0
	v_mfma_f32_16x16x32_f16 v[110:113], v[168:171], v[196:199], 0
	v_mfma_f32_16x16x32_f16 v[102:105], v[164:167], v[204:207], 0
	v_mfma_f32_16x16x32_f16 v[94:97], v[168:171], v[204:207], 0
	v_mfma_f32_16x16x32_f16 v[86:89], v[164:167], v[216:219], 0
	v_mfma_f32_16x16x32_f16 v[78:81], v[168:171], v[216:219], 0
	v_mfma_f32_16x16x32_f16 v[66:69], v[164:167], v[220:223], 0
	v_mfma_f32_16x16x32_f16 v[58:61], v[168:171], v[220:223], 0
	v_mfma_f32_16x16x32_f16 v[118:121], v[172:175], v[208:211], v[118:121]
	v_mfma_f32_16x16x32_f16 v[110:113], v[176:179], v[208:211], v[110:113]
	v_mfma_f32_16x16x32_f16 v[102:105], v[172:175], v[212:215], v[102:105]
	v_mfma_f32_16x16x32_f16 v[94:97], v[176:179], v[212:215], v[94:97]
	v_mfma_f32_16x16x32_f16 v[86:89], v[172:175], v[224:227], v[86:89]
	v_mfma_f32_16x16x32_f16 v[78:81], v[176:179], v[224:227], v[78:81]
	v_mfma_f32_16x16x32_f16 v[66:69], v[172:175], v[228:231], v[66:69]
	v_mfma_f32_16x16x32_f16 v[58:61], v[176:179], v[228:231], v[58:61]
	v_mfma_f32_16x16x32_f16 v[126:129], v[180:183], v[196:199], 0
	v_mfma_f32_16x16x32_f16 v[122:125], v[184:187], v[196:199], 0
	v_mfma_f32_16x16x32_f16 v[114:117], v[180:183], v[204:207], 0
	v_mfma_f32_16x16x32_f16 v[106:109], v[184:187], v[204:207], 0
	v_mfma_f32_16x16x32_f16 v[98:101], v[180:183], v[216:219], 0
	v_mfma_f32_16x16x32_f16 v[90:93], v[184:187], v[216:219], 0
	v_mfma_f32_16x16x32_f16 v[82:85], v[180:183], v[220:223], 0
	v_mfma_f32_16x16x32_f16 v[74:77], v[184:187], v[220:223], 0
	v_mfma_f32_16x16x32_f16 v[126:129], v[188:191], v[208:211], v[126:129]
	v_mfma_f32_16x16x32_f16 v[122:125], v[192:195], v[208:211], v[122:125]
	v_mfma_f32_16x16x32_f16 v[114:117], v[188:191], v[212:215], v[114:117]
	v_mfma_f32_16x16x32_f16 v[106:109], v[192:195], v[212:215], v[106:109]
	v_mfma_f32_16x16x32_f16 v[98:101], v[188:191], v[224:227], v[98:101]
	v_mfma_f32_16x16x32_f16 v[90:93], v[192:195], v[224:227], v[90:93]
	v_mfma_f32_16x16x32_f16 v[82:85], v[188:191], v[228:231], v[82:85]
	v_mfma_f32_16x16x32_f16 v[74:77], v[192:195], v[228:231], v[74:77]
	s_barrier
	s_mov_b32 s10, s50
	s_mov_b32 s11, s51
	s_mov_b32 m0, s26
	s_nop 0
	buffer_load_dwordx4 v154, s[8:11], s62 offen lds
	s_mov_b32 m0, s27
	s_add_i32 s81, s62, 0x80000
	buffer_load_dwordx4 v156, s[8:11], s62 offen lds
	s_mov_b32 m0, s28
	s_nop 0
	buffer_load_dwordx4 v154, s[8:11], s81 offen lds
	s_mov_b32 m0, s29
	s_nop 0
	buffer_load_dwordx4 v156, s[8:11], s81 offen lds
	s_mov_b32 m0, s3
	s_nop 0
	buffer_load_dwordx4 v153, s[48:51], s78 offen lds
	s_mov_b32 m0, s30
	s_nop 0
	buffer_load_dwordx4 v155, s[48:51], s78 offen lds
	ds_read_b128 v[196:199], v161 offset:16384
	ds_read_b128 v[204:207], v161 offset:18432
	ds_read_b128 v[208:211], v162 offset:16384
	ds_read_b128 v[212:215], v162 offset:18432
	ds_read_b128 v[216:219], v161 offset:20480
	ds_read_b128 v[220:223], v161 offset:22528
	ds_read_b128 v[224:227], v162 offset:20480
	ds_read_b128 v[228:231], v162 offset:22528
	s_waitcnt vmcnt(8)
	s_waitcnt lgkmcnt(0)
	s_barrier
	s_waitcnt lgkmcnt(0)
	v_mfma_f32_16x16x32_f16 v[54:57], v[164:167], v[196:199], 0
	v_mfma_f32_16x16x32_f16 v[46:49], v[168:171], v[196:199], 0
	v_mfma_f32_16x16x32_f16 v[38:41], v[164:167], v[204:207], 0
	v_mfma_f32_16x16x32_f16 v[30:33], v[168:171], v[204:207], 0
	v_mfma_f32_16x16x32_f16 v[22:25], v[164:167], v[216:219], 0
	v_mfma_f32_16x16x32_f16 v[14:17], v[168:171], v[216:219], 0
	v_mfma_f32_16x16x32_f16 v[6:9], v[164:167], v[220:223], 0
	v_mfma_f32_16x16x32_f16 v[2:5], v[168:171], v[220:223], 0
	v_mfma_f32_16x16x32_f16 v[54:57], v[172:175], v[208:211], v[54:57]
	v_mfma_f32_16x16x32_f16 v[46:49], v[176:179], v[208:211], v[46:49]
	v_mfma_f32_16x16x32_f16 v[38:41], v[172:175], v[212:215], v[38:41]
	v_mfma_f32_16x16x32_f16 v[30:33], v[176:179], v[212:215], v[30:33]
	v_mfma_f32_16x16x32_f16 v[22:25], v[172:175], v[224:227], v[22:25]
	v_mfma_f32_16x16x32_f16 v[14:17], v[176:179], v[224:227], v[14:17]
	v_mfma_f32_16x16x32_f16 v[6:9], v[172:175], v[228:231], v[6:9]
	v_mfma_f32_16x16x32_f16 v[2:5], v[176:179], v[228:231], v[2:5]
	v_mfma_f32_16x16x32_f16 v[70:73], v[180:183], v[196:199], 0
	v_mfma_f32_16x16x32_f16 v[62:65], v[184:187], v[196:199], 0
	v_mfma_f32_16x16x32_f16 v[50:53], v[180:183], v[204:207], 0
	v_mfma_f32_16x16x32_f16 v[42:45], v[184:187], v[204:207], 0
	v_mfma_f32_16x16x32_f16 v[34:37], v[180:183], v[216:219], 0
	v_mfma_f32_16x16x32_f16 v[26:29], v[184:187], v[216:219], 0
	v_mfma_f32_16x16x32_f16 v[18:21], v[180:183], v[220:223], 0
	v_mfma_f32_16x16x32_f16 v[10:13], v[184:187], v[220:223], 0
	v_mfma_f32_16x16x32_f16 v[70:73], v[188:191], v[208:211], v[70:73]
	v_mfma_f32_16x16x32_f16 v[62:65], v[192:195], v[208:211], v[62:65]
	v_mfma_f32_16x16x32_f16 v[50:53], v[188:191], v[212:215], v[50:53]
	v_mfma_f32_16x16x32_f16 v[42:45], v[192:195], v[212:215], v[42:45]
	v_mfma_f32_16x16x32_f16 v[34:37], v[188:191], v[224:227], v[34:37]
	v_mfma_f32_16x16x32_f16 v[26:29], v[192:195], v[224:227], v[26:29]
	v_mfma_f32_16x16x32_f16 v[18:21], v[188:191], v[228:231], v[18:21]
	v_mfma_f32_16x16x32_f16 v[10:13], v[192:195], v[228:231], v[10:13]
	s_barrier
	s_add_i32 s81, 0, 0x18000
	v_add_u32_e32 v0, s81, v157
	v_add_u32_e32 v147, s81, v158
	s_add_i32 s81, 0, 0x1c000
	s_add_i32 s78, s78, 0x80000
	s_mov_b32 m0, s31
	s_nop 0
	buffer_load_dwordx4 v153, s[48:51], s78 offen lds
	s_mov_b32 m0, s34
	s_nop 0
	buffer_load_dwordx4 v155, s[48:51], s78 offen lds
	ds_read_b128 v[164:167], v0
	ds_read_b128 v[168:171], v0 offset:2048
	ds_read_b128 v[172:175], v147
	ds_read_b128 v[176:179], v147 offset:2048
	v_add_u32_e32 v0, s81, v157
	v_add_u32_e32 v147, s81, v158
	ds_read_b128 v[180:183], v0
	ds_read_b128 v[184:187], v0 offset:2048
	ds_read_b128 v[188:191], v147
	ds_read_b128 v[192:195], v147 offset:2048
	ds_read_b128 v[196:199], v161 offset:32768
	ds_read_b128 v[204:207], v161 offset:34816
	ds_read_b128 v[208:211], v162 offset:32768
	ds_read_b128 v[212:215], v162 offset:34816
	ds_read_b128 v[216:219], v161 offset:36864
	ds_read_b128 v[220:223], v161 offset:38912
	ds_read_b128 v[224:227], v162 offset:36864
	ds_read_b128 v[228:231], v162 offset:38912
	s_waitcnt vmcnt(8)
	s_waitcnt lgkmcnt(0)
	s_barrier
	s_waitcnt lgkmcnt(0)
	v_mfma_f32_16x16x32_f16 v[118:121], v[164:167], v[196:199], v[118:121]
	v_mfma_f32_16x16x32_f16 v[110:113], v[168:171], v[196:199], v[110:113]
	v_mfma_f32_16x16x32_f16 v[102:105], v[164:167], v[204:207], v[102:105]
	v_mfma_f32_16x16x32_f16 v[94:97], v[168:171], v[204:207], v[94:97]
	v_mfma_f32_16x16x32_f16 v[86:89], v[164:167], v[216:219], v[86:89]
	v_mfma_f32_16x16x32_f16 v[78:81], v[168:171], v[216:219], v[78:81]
	v_mfma_f32_16x16x32_f16 v[66:69], v[164:167], v[220:223], v[66:69]
	v_mfma_f32_16x16x32_f16 v[58:61], v[168:171], v[220:223], v[58:61]
	v_mfma_f32_16x16x32_f16 v[118:121], v[172:175], v[208:211], v[118:121]
	v_mfma_f32_16x16x32_f16 v[110:113], v[176:179], v[208:211], v[110:113]
	v_mfma_f32_16x16x32_f16 v[102:105], v[172:175], v[212:215], v[102:105]
	v_mfma_f32_16x16x32_f16 v[94:97], v[176:179], v[212:215], v[94:97]
	v_mfma_f32_16x16x32_f16 v[86:89], v[172:175], v[224:227], v[86:89]
	v_mfma_f32_16x16x32_f16 v[78:81], v[176:179], v[224:227], v[78:81]
	v_mfma_f32_16x16x32_f16 v[66:69], v[172:175], v[228:231], v[66:69]
	v_mfma_f32_16x16x32_f16 v[58:61], v[176:179], v[228:231], v[58:61]
	v_mfma_f32_16x16x32_f16 v[126:129], v[180:183], v[196:199], v[126:129]
	v_mfma_f32_16x16x32_f16 v[122:125], v[184:187], v[196:199], v[122:125]
	v_mfma_f32_16x16x32_f16 v[114:117], v[180:183], v[204:207], v[114:117]
	v_mfma_f32_16x16x32_f16 v[106:109], v[184:187], v[204:207], v[106:109]
	v_mfma_f32_16x16x32_f16 v[98:101], v[180:183], v[216:219], v[98:101]
	v_mfma_f32_16x16x32_f16 v[90:93], v[184:187], v[216:219], v[90:93]
	v_mfma_f32_16x16x32_f16 v[82:85], v[180:183], v[220:223], v[82:85]
	v_mfma_f32_16x16x32_f16 v[74:77], v[184:187], v[220:223], v[74:77]
	v_mfma_f32_16x16x32_f16 v[126:129], v[188:191], v[208:211], v[126:129]
	v_mfma_f32_16x16x32_f16 v[122:125], v[192:195], v[208:211], v[122:125]
	v_mfma_f32_16x16x32_f16 v[114:117], v[188:191], v[212:215], v[114:117]
	v_mfma_f32_16x16x32_f16 v[106:109], v[192:195], v[212:215], v[106:109]
	v_mfma_f32_16x16x32_f16 v[98:101], v[188:191], v[224:227], v[98:101]
	v_mfma_f32_16x16x32_f16 v[90:93], v[192:195], v[224:227], v[90:93]
	v_mfma_f32_16x16x32_f16 v[82:85], v[188:191], v[228:231], v[82:85]
	v_mfma_f32_16x16x32_f16 v[74:77], v[192:195], v[228:231], v[74:77]
	s_barrier
	s_mov_b32 m0, s35
	s_nop 0
	buffer_load_dwordx4 v154, s[8:11], s65 offen lds
	s_mov_b32 m0, s36
	s_add_i32 s62, s62, 0x80080
	buffer_load_dwordx4 v156, s[8:11], s65 offen lds
	s_mov_b32 m0, s39
	s_nop 0
	buffer_load_dwordx4 v154, s[8:11], s62 offen lds
	s_mov_b32 m0, s40
	s_nop 0
	buffer_load_dwordx4 v156, s[8:11], s62 offen lds
	s_mov_b32 m0, s37
	s_nop 0
	buffer_load_dwordx4 v153, s[48:51], s64 offen lds
	s_mov_b32 m0, s38
	s_nop 0
	buffer_load_dwordx4 v155, s[48:51], s64 offen lds
	ds_read_b128 v[196:199], v161 offset:49152
	ds_read_b128 v[204:207], v161 offset:51200
	ds_read_b128 v[208:211], v162 offset:49152
	ds_read_b128 v[212:215], v162 offset:51200
	ds_read_b128 v[216:219], v161 offset:53248
	ds_read_b128 v[220:223], v161 offset:55296
	ds_read_b128 v[224:227], v162 offset:53248
	ds_read_b128 v[228:231], v162 offset:55296
	s_waitcnt vmcnt(8)
	s_waitcnt lgkmcnt(0)
	s_barrier
	s_waitcnt lgkmcnt(0)
	v_mfma_f32_16x16x32_f16 v[54:57], v[164:167], v[196:199], v[54:57]
	v_mfma_f32_16x16x32_f16 v[46:49], v[168:171], v[196:199], v[46:49]
	v_mfma_f32_16x16x32_f16 v[38:41], v[164:167], v[204:207], v[38:41]
	v_mfma_f32_16x16x32_f16 v[30:33], v[168:171], v[204:207], v[30:33]
	v_mfma_f32_16x16x32_f16 v[22:25], v[164:167], v[216:219], v[22:25]
	v_mfma_f32_16x16x32_f16 v[14:17], v[168:171], v[216:219], v[14:17]
	v_mfma_f32_16x16x32_f16 v[6:9], v[164:167], v[220:223], v[6:9]
	v_mfma_f32_16x16x32_f16 v[2:5], v[168:171], v[220:223], v[2:5]
	v_mfma_f32_16x16x32_f16 v[54:57], v[172:175], v[208:211], v[54:57]
	v_mfma_f32_16x16x32_f16 v[46:49], v[176:179], v[208:211], v[46:49]
	v_mfma_f32_16x16x32_f16 v[38:41], v[172:175], v[212:215], v[38:41]
	v_mfma_f32_16x16x32_f16 v[30:33], v[176:179], v[212:215], v[30:33]
	v_mfma_f32_16x16x32_f16 v[22:25], v[172:175], v[224:227], v[22:25]
	v_mfma_f32_16x16x32_f16 v[14:17], v[176:179], v[224:227], v[14:17]
	v_mfma_f32_16x16x32_f16 v[6:9], v[172:175], v[228:231], v[6:9]
	v_mfma_f32_16x16x32_f16 v[2:5], v[176:179], v[228:231], v[2:5]
	v_mfma_f32_16x16x32_f16 v[70:73], v[180:183], v[196:199], v[70:73]
	v_mfma_f32_16x16x32_f16 v[62:65], v[184:187], v[196:199], v[62:65]
	v_mfma_f32_16x16x32_f16 v[50:53], v[180:183], v[204:207], v[50:53]
	v_mfma_f32_16x16x32_f16 v[42:45], v[184:187], v[204:207], v[42:45]
	v_mfma_f32_16x16x32_f16 v[34:37], v[180:183], v[216:219], v[34:37]
	v_mfma_f32_16x16x32_f16 v[26:29], v[184:187], v[216:219], v[26:29]
	v_mfma_f32_16x16x32_f16 v[18:21], v[180:183], v[220:223], v[18:21]
	v_mfma_f32_16x16x32_f16 v[10:13], v[184:187], v[220:223], v[10:13]
	v_mfma_f32_16x16x32_f16 v[70:73], v[188:191], v[208:211], v[70:73]
	v_mfma_f32_16x16x32_f16 v[62:65], v[192:195], v[208:211], v[62:65]
	v_mfma_f32_16x16x32_f16 v[50:53], v[188:191], v[212:215], v[50:53]
	v_mfma_f32_16x16x32_f16 v[42:45], v[192:195], v[212:215], v[42:45]
	v_mfma_f32_16x16x32_f16 v[34:37], v[188:191], v[224:227], v[34:37]
	v_mfma_f32_16x16x32_f16 v[26:29], v[192:195], v[224:227], v[26:29]
	v_mfma_f32_16x16x32_f16 v[18:21], v[188:191], v[228:231], v[18:21]
	v_mfma_f32_16x16x32_f16 v[10:13], v[192:195], v[228:231], v[10:13]
	s_barrier
	s_branch .Lc0s_tail
.Lc0s_final:
	s_add_i32 s62, s58, 0xfff80080
	s_and_b64 s[10:11], s[10:11], exec
	s_cselect_b32 s78, s54, s62
	s_cselect_b32 s62, s55, s60
	s_add_i32 s10, 0, 0x10000
	v_add_u32_e32 v0, s10, v157
	v_add_u32_e32 v147, s10, v158
	s_add_i32 s10, 0, 0x14000
	s_mov_b32 m0, s41
	s_nop 0
	buffer_load_dwordx4 v153, s[48:51], s58 offen lds
	s_mov_b32 m0, s42
	s_nop 0
	buffer_load_dwordx4 v155, s[48:51], s58 offen lds
	ds_read_b128 v[164:167], v0
	ds_read_b128 v[168:171], v0 offset:2048
	ds_read_b128 v[172:175], v147
	ds_read_b128 v[176:179], v147 offset:2048
	v_add_u32_e32 v0, s10, v157
	v_add_u32_e32 v147, s10, v158
	ds_read_b128 v[180:183], v0
	ds_read_b128 v[184:187], v0 offset:2048
	ds_read_b128 v[188:191], v147
	ds_read_b128 v[192:195], v147 offset:2048
	s_or_b32 s64, s78, 0x80
	s_or_b32 s65, s62, 0x80
	ds_read_b128 v[196:199], v161
	ds_read_b128 v[204:207], v161 offset:2048
	ds_read_b128 v[208:211], v162
	ds_read_b128 v[212:215], v162 offset:2048
	ds_read_b128 v[216:219], v161 offset:4096
	ds_read_b128 v[220:223], v161 offset:6144
	ds_read_b128 v[224:227], v162 offset:4096
	ds_read_b128 v[228:231], v162 offset:6144
	s_waitcnt vmcnt(8)
	s_waitcnt lgkmcnt(0)
	s_barrier
	s_waitcnt lgkmcnt(0)
	v_mfma_f32_16x16x32_f16 v[118:121], v[164:167], v[196:199], v[118:121]
	v_mfma_f32_16x16x32_f16 v[110:113], v[168:171], v[196:199], v[110:113]
	v_mfma_f32_16x16x32_f16 v[102:105], v[164:167], v[204:207], v[102:105]
	v_mfma_f32_16x16x32_f16 v[94:97], v[168:171], v[204:207], v[94:97]
	v_mfma_f32_16x16x32_f16 v[86:89], v[164:167], v[216:219], v[86:89]
	v_mfma_f32_16x16x32_f16 v[78:81], v[168:171], v[216:219], v[78:81]
	v_mfma_f32_16x16x32_f16 v[66:69], v[164:167], v[220:223], v[66:69]
	v_mfma_f32_16x16x32_f16 v[58:61], v[168:171], v[220:223], v[58:61]
	v_mfma_f32_16x16x32_f16 v[118:121], v[172:175], v[208:211], v[118:121]
	v_mfma_f32_16x16x32_f16 v[110:113], v[176:179], v[208:211], v[110:113]
	v_mfma_f32_16x16x32_f16 v[102:105], v[172:175], v[212:215], v[102:105]
	v_mfma_f32_16x16x32_f16 v[94:97], v[176:179], v[212:215], v[94:97]
	v_mfma_f32_16x16x32_f16 v[86:89], v[172:175], v[224:227], v[86:89]
	v_mfma_f32_16x16x32_f16 v[78:81], v[176:179], v[224:227], v[78:81]
	v_mfma_f32_16x16x32_f16 v[66:69], v[172:175], v[228:231], v[66:69]
	v_mfma_f32_16x16x32_f16 v[58:61], v[176:179], v[228:231], v[58:61]
	v_mfma_f32_16x16x32_f16 v[126:129], v[180:183], v[196:199], v[126:129]
	v_mfma_f32_16x16x32_f16 v[122:125], v[184:187], v[196:199], v[122:125]
	v_mfma_f32_16x16x32_f16 v[114:117], v[180:183], v[204:207], v[114:117]
	v_mfma_f32_16x16x32_f16 v[106:109], v[184:187], v[204:207], v[106:109]
	v_mfma_f32_16x16x32_f16 v[98:101], v[180:183], v[216:219], v[98:101]
	v_mfma_f32_16x16x32_f16 v[90:93], v[184:187], v[216:219], v[90:93]
	v_mfma_f32_16x16x32_f16 v[82:85], v[180:183], v[220:223], v[82:85]
	v_mfma_f32_16x16x32_f16 v[74:77], v[184:187], v[220:223], v[74:77]
	v_mfma_f32_16x16x32_f16 v[126:129], v[188:191], v[208:211], v[126:129]
	v_mfma_f32_16x16x32_f16 v[122:125], v[192:195], v[208:211], v[122:125]
	v_mfma_f32_16x16x32_f16 v[114:117], v[188:191], v[212:215], v[114:117]
	v_mfma_f32_16x16x32_f16 v[106:109], v[192:195], v[212:215], v[106:109]
	v_mfma_f32_16x16x32_f16 v[98:101], v[188:191], v[224:227], v[98:101]
	v_mfma_f32_16x16x32_f16 v[90:93], v[192:195], v[224:227], v[90:93]
	v_mfma_f32_16x16x32_f16 v[82:85], v[188:191], v[228:231], v[82:85]
	v_mfma_f32_16x16x32_f16 v[74:77], v[192:195], v[228:231], v[74:77]
	s_barrier
	s_mov_b32 s10, s50
	s_mov_b32 s11, s51
	ds_read_b128 v[196:199], v161 offset:16384
	ds_read_b128 v[204:207], v161 offset:18432
	ds_read_b128 v[208:211], v162 offset:16384
	ds_read_b128 v[212:215], v162 offset:18432
	ds_read_b128 v[216:219], v161 offset:20480
	ds_read_b128 v[220:223], v161 offset:22528
	ds_read_b128 v[224:227], v162 offset:20480
	ds_read_b128 v[228:231], v162 offset:22528
	s_add_i32 s81, s62, 0x80000
	s_waitcnt vmcnt(2)
	s_waitcnt lgkmcnt(0)
	s_barrier
	s_waitcnt lgkmcnt(0)
	v_mfma_f32_16x16x32_f16 v[54:57], v[164:167], v[196:199], v[54:57]
	v_mfma_f32_16x16x32_f16 v[46:49], v[168:171], v[196:199], v[46:49]
	v_mfma_f32_16x16x32_f16 v[38:41], v[164:167], v[204:207], v[38:41]
	v_mfma_f32_16x16x32_f16 v[30:33], v[168:171], v[204:207], v[30:33]
	v_mfma_f32_16x16x32_f16 v[22:25], v[164:167], v[216:219], v[22:25]
	v_mfma_f32_16x16x32_f16 v[14:17], v[168:171], v[216:219], v[14:17]
	v_mfma_f32_16x16x32_f16 v[6:9], v[164:167], v[220:223], v[6:9]
	v_mfma_f32_16x16x32_f16 v[2:5], v[168:171], v[220:223], v[2:5]
	v_mfma_f32_16x16x32_f16 v[54:57], v[172:175], v[208:211], v[54:57]
	v_mfma_f32_16x16x32_f16 v[46:49], v[176:179], v[208:211], v[46:49]
	v_mfma_f32_16x16x32_f16 v[38:41], v[172:175], v[212:215], v[38:41]
	v_mfma_f32_16x16x32_f16 v[30:33], v[176:179], v[212:215], v[30:33]
	v_mfma_f32_16x16x32_f16 v[22:25], v[172:175], v[224:227], v[22:25]
	v_mfma_f32_16x16x32_f16 v[14:17], v[176:179], v[224:227], v[14:17]
	v_mfma_f32_16x16x32_f16 v[6:9], v[172:175], v[228:231], v[6:9]
	v_mfma_f32_16x16x32_f16 v[2:5], v[176:179], v[228:231], v[2:5]
	v_mfma_f32_16x16x32_f16 v[70:73], v[180:183], v[196:199], v[70:73]
	v_mfma_f32_16x16x32_f16 v[62:65], v[184:187], v[196:199], v[62:65]
	v_mfma_f32_16x16x32_f16 v[50:53], v[180:183], v[204:207], v[50:53]
	v_mfma_f32_16x16x32_f16 v[42:45], v[184:187], v[204:207], v[42:45]
	v_mfma_f32_16x16x32_f16 v[34:37], v[180:183], v[216:219], v[34:37]
	v_mfma_f32_16x16x32_f16 v[26:29], v[184:187], v[216:219], v[26:29]
	v_mfma_f32_16x16x32_f16 v[18:21], v[180:183], v[220:223], v[18:21]
	v_mfma_f32_16x16x32_f16 v[10:13], v[184:187], v[220:223], v[10:13]
	v_mfma_f32_16x16x32_f16 v[70:73], v[188:191], v[208:211], v[70:73]
	v_mfma_f32_16x16x32_f16 v[62:65], v[192:195], v[208:211], v[62:65]
	v_mfma_f32_16x16x32_f16 v[50:53], v[188:191], v[212:215], v[50:53]
	v_mfma_f32_16x16x32_f16 v[42:45], v[192:195], v[212:215], v[42:45]
	v_mfma_f32_16x16x32_f16 v[34:37], v[188:191], v[224:227], v[34:37]
	v_mfma_f32_16x16x32_f16 v[26:29], v[192:195], v[224:227], v[26:29]
	v_mfma_f32_16x16x32_f16 v[18:21], v[188:191], v[228:231], v[18:21]
	v_mfma_f32_16x16x32_f16 v[10:13], v[192:195], v[228:231], v[10:13]
	s_barrier
	s_add_i32 s81, 0, 0x18000
	v_add_u32_e32 v0, s81, v157
	v_add_u32_e32 v147, s81, v158
	s_add_i32 s81, 0, 0x1c000
	ds_read_b128 v[164:167], v0
	ds_read_b128 v[168:171], v0 offset:2048
	ds_read_b128 v[172:175], v147
	ds_read_b128 v[176:179], v147 offset:2048
	v_add_u32_e32 v0, s81, v157
	v_add_u32_e32 v147, s81, v158
	ds_read_b128 v[180:183], v0
	ds_read_b128 v[184:187], v0 offset:2048
	ds_read_b128 v[188:191], v147
	ds_read_b128 v[192:195], v147 offset:2048
	s_add_i32 s78, s78, 0x80000
	ds_read_b128 v[196:199], v161 offset:32768
	ds_read_b128 v[204:207], v161 offset:34816
	ds_read_b128 v[208:211], v162 offset:32768
	ds_read_b128 v[212:215], v162 offset:34816
	ds_read_b128 v[216:219], v161 offset:36864
	ds_read_b128 v[220:223], v161 offset:38912
	ds_read_b128 v[224:227], v162 offset:36864
	ds_read_b128 v[228:231], v162 offset:38912
	s_waitcnt vmcnt(0)
	s_waitcnt lgkmcnt(0)
	s_barrier
	s_waitcnt lgkmcnt(0)
	v_mfma_f32_16x16x32_f16 v[118:121], v[164:167], v[196:199], v[118:121]
	v_mfma_f32_16x16x32_f16 v[110:113], v[168:171], v[196:199], v[110:113]
	v_mfma_f32_16x16x32_f16 v[102:105], v[164:167], v[204:207], v[102:105]
	v_mfma_f32_16x16x32_f16 v[94:97], v[168:171], v[204:207], v[94:97]
	v_mfma_f32_16x16x32_f16 v[86:89], v[164:167], v[216:219], v[86:89]
	v_mfma_f32_16x16x32_f16 v[78:81], v[168:171], v[216:219], v[78:81]
	v_mfma_f32_16x16x32_f16 v[66:69], v[164:167], v[220:223], v[66:69]
	v_mfma_f32_16x16x32_f16 v[58:61], v[168:171], v[220:223], v[58:61]
	v_mfma_f32_16x16x32_f16 v[118:121], v[172:175], v[208:211], v[118:121]
	v_mfma_f32_16x16x32_f16 v[110:113], v[176:179], v[208:211], v[110:113]
	v_mfma_f32_16x16x32_f16 v[102:105], v[172:175], v[212:215], v[102:105]
	v_mfma_f32_16x16x32_f16 v[94:97], v[176:179], v[212:215], v[94:97]
	v_mfma_f32_16x16x32_f16 v[86:89], v[172:175], v[224:227], v[86:89]
	v_mfma_f32_16x16x32_f16 v[78:81], v[176:179], v[224:227], v[78:81]
	v_mfma_f32_16x16x32_f16 v[66:69], v[172:175], v[228:231], v[66:69]
	v_mfma_f32_16x16x32_f16 v[58:61], v[176:179], v[228:231], v[58:61]
	v_mfma_f32_16x16x32_f16 v[126:129], v[180:183], v[196:199], v[126:129]
	v_mfma_f32_16x16x32_f16 v[122:125], v[184:187], v[196:199], v[122:125]
	v_mfma_f32_16x16x32_f16 v[114:117], v[180:183], v[204:207], v[114:117]
	v_mfma_f32_16x16x32_f16 v[106:109], v[184:187], v[204:207], v[106:109]
	v_mfma_f32_16x16x32_f16 v[98:101], v[180:183], v[216:219], v[98:101]
	v_mfma_f32_16x16x32_f16 v[90:93], v[184:187], v[216:219], v[90:93]
	v_mfma_f32_16x16x32_f16 v[82:85], v[180:183], v[220:223], v[82:85]
	v_mfma_f32_16x16x32_f16 v[74:77], v[184:187], v[220:223], v[74:77]
	v_mfma_f32_16x16x32_f16 v[126:129], v[188:191], v[208:211], v[126:129]
	v_mfma_f32_16x16x32_f16 v[122:125], v[192:195], v[208:211], v[122:125]
	v_mfma_f32_16x16x32_f16 v[114:117], v[188:191], v[212:215], v[114:117]
	v_mfma_f32_16x16x32_f16 v[106:109], v[192:195], v[212:215], v[106:109]
	v_mfma_f32_16x16x32_f16 v[98:101], v[188:191], v[224:227], v[98:101]
	v_mfma_f32_16x16x32_f16 v[90:93], v[192:195], v[224:227], v[90:93]
	v_mfma_f32_16x16x32_f16 v[82:85], v[188:191], v[228:231], v[82:85]
	v_mfma_f32_16x16x32_f16 v[74:77], v[192:195], v[228:231], v[74:77]
	s_barrier
	ds_read_b128 v[196:199], v161 offset:49152
	ds_read_b128 v[204:207], v161 offset:51200
	ds_read_b128 v[208:211], v162 offset:49152
	ds_read_b128 v[212:215], v162 offset:51200
	ds_read_b128 v[216:219], v161 offset:53248
	ds_read_b128 v[220:223], v161 offset:55296
	ds_read_b128 v[224:227], v162 offset:53248
	ds_read_b128 v[228:231], v162 offset:55296
	s_add_i32 s62, s62, 0x80080
	s_waitcnt vmcnt(0)
	s_waitcnt lgkmcnt(0)
	s_barrier
	s_waitcnt lgkmcnt(0)
	v_mfma_f32_16x16x32_f16 v[54:57], v[164:167], v[196:199], v[54:57]
	v_mfma_f32_16x16x32_f16 v[46:49], v[168:171], v[196:199], v[46:49]
	v_mfma_f32_16x16x32_f16 v[38:41], v[164:167], v[204:207], v[38:41]
	v_mfma_f32_16x16x32_f16 v[30:33], v[168:171], v[204:207], v[30:33]
	v_mfma_f32_16x16x32_f16 v[22:25], v[164:167], v[216:219], v[22:25]
	v_mfma_f32_16x16x32_f16 v[14:17], v[168:171], v[216:219], v[14:17]
	v_mfma_f32_16x16x32_f16 v[6:9], v[164:167], v[220:223], v[6:9]
	v_mfma_f32_16x16x32_f16 v[2:5], v[168:171], v[220:223], v[2:5]
	v_mfma_f32_16x16x32_f16 v[54:57], v[172:175], v[208:211], v[54:57]
	v_mfma_f32_16x16x32_f16 v[46:49], v[176:179], v[208:211], v[46:49]
	v_mfma_f32_16x16x32_f16 v[38:41], v[172:175], v[212:215], v[38:41]
	v_mfma_f32_16x16x32_f16 v[30:33], v[176:179], v[212:215], v[30:33]
	v_mfma_f32_16x16x32_f16 v[22:25], v[172:175], v[224:227], v[22:25]
	v_mfma_f32_16x16x32_f16 v[14:17], v[176:179], v[224:227], v[14:17]
	v_mfma_f32_16x16x32_f16 v[6:9], v[172:175], v[228:231], v[6:9]
	v_mfma_f32_16x16x32_f16 v[2:5], v[176:179], v[228:231], v[2:5]
	v_mfma_f32_16x16x32_f16 v[70:73], v[180:183], v[196:199], v[70:73]
	v_mfma_f32_16x16x32_f16 v[62:65], v[184:187], v[196:199], v[62:65]
	v_mfma_f32_16x16x32_f16 v[50:53], v[180:183], v[204:207], v[50:53]
	v_mfma_f32_16x16x32_f16 v[42:45], v[184:187], v[204:207], v[42:45]
	v_mfma_f32_16x16x32_f16 v[34:37], v[180:183], v[216:219], v[34:37]
	v_mfma_f32_16x16x32_f16 v[26:29], v[184:187], v[216:219], v[26:29]
	v_mfma_f32_16x16x32_f16 v[18:21], v[180:183], v[220:223], v[18:21]
	v_mfma_f32_16x16x32_f16 v[10:13], v[184:187], v[220:223], v[10:13]
	v_mfma_f32_16x16x32_f16 v[70:73], v[188:191], v[208:211], v[70:73]
	v_mfma_f32_16x16x32_f16 v[62:65], v[192:195], v[208:211], v[62:65]
	v_mfma_f32_16x16x32_f16 v[50:53], v[188:191], v[212:215], v[50:53]
	v_mfma_f32_16x16x32_f16 v[42:45], v[192:195], v[212:215], v[42:45]
	v_mfma_f32_16x16x32_f16 v[34:37], v[188:191], v[224:227], v[34:37]
	v_mfma_f32_16x16x32_f16 v[26:29], v[192:195], v[224:227], v[26:29]
	v_mfma_f32_16x16x32_f16 v[18:21], v[188:191], v[228:231], v[18:21]
	v_mfma_f32_16x16x32_f16 v[10:13], v[192:195], v[228:231], v[10:13]
	s_barrier
	s_branch .Lc0s_tail

.Lc0s_norm:
	s_add_i32 s62, s58, 0xfff80080
	s_and_b64 s[10:11], s[10:11], exec
	s_cselect_b32 s78, s54, s62
	s_cselect_b32 s62, s55, s60
	s_add_i32 s10, 0, 0x10000
	v_add_u32_e32 v0, s10, v157
	v_add_u32_e32 v147, s10, v158
	s_add_i32 s10, 0, 0x14000
	s_mov_b32 m0, s41
	s_nop 0
	buffer_load_dwordx4 v153, s[48:51], s58 offen lds
	s_mov_b32 m0, s42
	s_nop 0
	buffer_load_dwordx4 v155, s[48:51], s58 offen lds
	ds_read_b128 v[164:167], v0
	ds_read_b128 v[168:171], v0 offset:2048
	ds_read_b128 v[172:175], v147
	ds_read_b128 v[176:179], v147 offset:2048
	v_add_u32_e32 v0, s10, v157
	v_add_u32_e32 v147, s10, v158
	ds_read_b128 v[180:183], v0
	ds_read_b128 v[184:187], v0 offset:2048
	ds_read_b128 v[188:191], v147
	ds_read_b128 v[192:195], v147 offset:2048
	s_or_b32 s64, s78, 0x80
	s_or_b32 s65, s62, 0x80
	ds_read_b128 v[196:199], v161
	ds_read_b128 v[204:207], v161 offset:2048
	ds_read_b128 v[208:211], v162
	ds_read_b128 v[212:215], v162 offset:2048
	ds_read_b128 v[216:219], v161 offset:4096
	ds_read_b128 v[220:223], v161 offset:6144
	ds_read_b128 v[224:227], v162 offset:4096
	ds_read_b128 v[228:231], v162 offset:6144
	s_waitcnt vmcnt(8)
	s_waitcnt lgkmcnt(0)
	s_barrier
	s_waitcnt lgkmcnt(0)
	v_mfma_f32_16x16x32_f16 v[118:121], v[164:167], v[196:199], v[118:121]
	v_mfma_f32_16x16x32_f16 v[110:113], v[168:171], v[196:199], v[110:113]
	v_mfma_f32_16x16x32_f16 v[102:105], v[164:167], v[204:207], v[102:105]
	v_mfma_f32_16x16x32_f16 v[94:97], v[168:171], v[204:207], v[94:97]
	v_mfma_f32_16x16x32_f16 v[86:89], v[164:167], v[216:219], v[86:89]
	v_mfma_f32_16x16x32_f16 v[78:81], v[168:171], v[216:219], v[78:81]
	v_mfma_f32_16x16x32_f16 v[66:69], v[164:167], v[220:223], v[66:69]
	v_mfma_f32_16x16x32_f16 v[58:61], v[168:171], v[220:223], v[58:61]
	v_mfma_f32_16x16x32_f16 v[118:121], v[172:175], v[208:211], v[118:121]
	v_mfma_f32_16x16x32_f16 v[110:113], v[176:179], v[208:211], v[110:113]
	v_mfma_f32_16x16x32_f16 v[102:105], v[172:175], v[212:215], v[102:105]
	v_mfma_f32_16x16x32_f16 v[94:97], v[176:179], v[212:215], v[94:97]
	v_mfma_f32_16x16x32_f16 v[86:89], v[172:175], v[224:227], v[86:89]
	v_mfma_f32_16x16x32_f16 v[78:81], v[176:179], v[224:227], v[78:81]
	v_mfma_f32_16x16x32_f16 v[66:69], v[172:175], v[228:231], v[66:69]
	v_mfma_f32_16x16x32_f16 v[58:61], v[176:179], v[228:231], v[58:61]
	v_mfma_f32_16x16x32_f16 v[126:129], v[180:183], v[196:199], v[126:129]
	v_mfma_f32_16x16x32_f16 v[122:125], v[184:187], v[196:199], v[122:125]
	v_mfma_f32_16x16x32_f16 v[114:117], v[180:183], v[204:207], v[114:117]
	v_mfma_f32_16x16x32_f16 v[106:109], v[184:187], v[204:207], v[106:109]
	v_mfma_f32_16x16x32_f16 v[98:101], v[180:183], v[216:219], v[98:101]
	v_mfma_f32_16x16x32_f16 v[90:93], v[184:187], v[216:219], v[90:93]
	v_mfma_f32_16x16x32_f16 v[82:85], v[180:183], v[220:223], v[82:85]
	v_mfma_f32_16x16x32_f16 v[74:77], v[184:187], v[220:223], v[74:77]
	v_mfma_f32_16x16x32_f16 v[126:129], v[188:191], v[208:211], v[126:129]
	v_mfma_f32_16x16x32_f16 v[122:125], v[192:195], v[208:211], v[122:125]
	v_mfma_f32_16x16x32_f16 v[114:117], v[188:191], v[212:215], v[114:117]
	v_mfma_f32_16x16x32_f16 v[106:109], v[192:195], v[212:215], v[106:109]
	v_mfma_f32_16x16x32_f16 v[98:101], v[188:191], v[224:227], v[98:101]
	v_mfma_f32_16x16x32_f16 v[90:93], v[192:195], v[224:227], v[90:93]
	v_mfma_f32_16x16x32_f16 v[82:85], v[188:191], v[228:231], v[82:85]
	v_mfma_f32_16x16x32_f16 v[74:77], v[192:195], v[228:231], v[74:77]
	s_barrier
	s_mov_b32 s10, s50
	s_mov_b32 s11, s51
	s_mov_b32 m0, s26
	s_nop 0
	buffer_load_dwordx4 v154, s[8:11], s62 offen lds
	s_mov_b32 m0, s27
	s_add_i32 s81, s62, 0x80000
	buffer_load_dwordx4 v156, s[8:11], s62 offen lds
	s_mov_b32 m0, s28
	s_nop 0
	buffer_load_dwordx4 v154, s[8:11], s81 offen lds
	s_mov_b32 m0, s29
	s_nop 0
	buffer_load_dwordx4 v156, s[8:11], s81 offen lds
	s_mov_b32 m0, s3
	s_nop 0
	buffer_load_dwordx4 v153, s[48:51], s78 offen lds
	s_mov_b32 m0, s30
	s_nop 0
	buffer_load_dwordx4 v155, s[48:51], s78 offen lds
	ds_read_b128 v[196:199], v161 offset:16384
	ds_read_b128 v[204:207], v161 offset:18432
	ds_read_b128 v[208:211], v162 offset:16384
	ds_read_b128 v[212:215], v162 offset:18432
	ds_read_b128 v[216:219], v161 offset:20480
	ds_read_b128 v[220:223], v161 offset:22528
	ds_read_b128 v[224:227], v162 offset:20480
	ds_read_b128 v[228:231], v162 offset:22528
	s_waitcnt vmcnt(8)
	s_waitcnt lgkmcnt(0)
	s_barrier
	s_waitcnt lgkmcnt(0)
	v_mfma_f32_16x16x32_f16 v[54:57], v[164:167], v[196:199], v[54:57]
	v_mfma_f32_16x16x32_f16 v[46:49], v[168:171], v[196:199], v[46:49]
	v_mfma_f32_16x16x32_f16 v[38:41], v[164:167], v[204:207], v[38:41]
	v_mfma_f32_16x16x32_f16 v[30:33], v[168:171], v[204:207], v[30:33]
	v_mfma_f32_16x16x32_f16 v[22:25], v[164:167], v[216:219], v[22:25]
	v_mfma_f32_16x16x32_f16 v[14:17], v[168:171], v[216:219], v[14:17]
	v_mfma_f32_16x16x32_f16 v[6:9], v[164:167], v[220:223], v[6:9]
	v_mfma_f32_16x16x32_f16 v[2:5], v[168:171], v[220:223], v[2:5]
	v_mfma_f32_16x16x32_f16 v[54:57], v[172:175], v[208:211], v[54:57]
	v_mfma_f32_16x16x32_f16 v[46:49], v[176:179], v[208:211], v[46:49]
	v_mfma_f32_16x16x32_f16 v[38:41], v[172:175], v[212:215], v[38:41]
	v_mfma_f32_16x16x32_f16 v[30:33], v[176:179], v[212:215], v[30:33]
	v_mfma_f32_16x16x32_f16 v[22:25], v[172:175], v[224:227], v[22:25]
	v_mfma_f32_16x16x32_f16 v[14:17], v[176:179], v[224:227], v[14:17]
	v_mfma_f32_16x16x32_f16 v[6:9], v[172:175], v[228:231], v[6:9]
	v_mfma_f32_16x16x32_f16 v[2:5], v[176:179], v[228:231], v[2:5]
	v_mfma_f32_16x16x32_f16 v[70:73], v[180:183], v[196:199], v[70:73]
	v_mfma_f32_16x16x32_f16 v[62:65], v[184:187], v[196:199], v[62:65]
	v_mfma_f32_16x16x32_f16 v[50:53], v[180:183], v[204:207], v[50:53]
	v_mfma_f32_16x16x32_f16 v[42:45], v[184:187], v[204:207], v[42:45]
	v_mfma_f32_16x16x32_f16 v[34:37], v[180:183], v[216:219], v[34:37]
	v_mfma_f32_16x16x32_f16 v[26:29], v[184:187], v[216:219], v[26:29]
	v_mfma_f32_16x16x32_f16 v[18:21], v[180:183], v[220:223], v[18:21]
	v_mfma_f32_16x16x32_f16 v[10:13], v[184:187], v[220:223], v[10:13]
	v_mfma_f32_16x16x32_f16 v[70:73], v[188:191], v[208:211], v[70:73]
	v_mfma_f32_16x16x32_f16 v[62:65], v[192:195], v[208:211], v[62:65]
	v_mfma_f32_16x16x32_f16 v[50:53], v[188:191], v[212:215], v[50:53]
	v_mfma_f32_16x16x32_f16 v[42:45], v[192:195], v[212:215], v[42:45]
	v_mfma_f32_16x16x32_f16 v[34:37], v[188:191], v[224:227], v[34:37]
	v_mfma_f32_16x16x32_f16 v[26:29], v[192:195], v[224:227], v[26:29]
	v_mfma_f32_16x16x32_f16 v[18:21], v[188:191], v[228:231], v[18:21]
	v_mfma_f32_16x16x32_f16 v[10:13], v[192:195], v[228:231], v[10:13]
	s_barrier
	s_add_i32 s81, 0, 0x18000
	v_add_u32_e32 v0, s81, v157
	v_add_u32_e32 v147, s81, v158
	s_add_i32 s81, 0, 0x1c000
	s_add_i32 s78, s78, 0x80000
	s_mov_b32 m0, s31
	s_nop 0
	buffer_load_dwordx4 v153, s[48:51], s78 offen lds
	s_mov_b32 m0, s34
	s_nop 0
	buffer_load_dwordx4 v155, s[48:51], s78 offen lds
	ds_read_b128 v[164:167], v0
	ds_read_b128 v[168:171], v0 offset:2048
	ds_read_b128 v[172:175], v147
	ds_read_b128 v[176:179], v147 offset:2048
	v_add_u32_e32 v0, s81, v157
	v_add_u32_e32 v147, s81, v158
	ds_read_b128 v[180:183], v0
	ds_read_b128 v[184:187], v0 offset:2048
	ds_read_b128 v[188:191], v147
	ds_read_b128 v[192:195], v147 offset:2048
	ds_read_b128 v[196:199], v161 offset:32768
	ds_read_b128 v[204:207], v161 offset:34816
	ds_read_b128 v[208:211], v162 offset:32768
	ds_read_b128 v[212:215], v162 offset:34816
	ds_read_b128 v[216:219], v161 offset:36864
	ds_read_b128 v[220:223], v161 offset:38912
	ds_read_b128 v[224:227], v162 offset:36864
	ds_read_b128 v[228:231], v162 offset:38912
	s_waitcnt vmcnt(8)
	s_waitcnt lgkmcnt(0)
	s_barrier
	s_waitcnt lgkmcnt(0)
	v_mfma_f32_16x16x32_f16 v[118:121], v[164:167], v[196:199], v[118:121]
	v_mfma_f32_16x16x32_f16 v[110:113], v[168:171], v[196:199], v[110:113]
	v_mfma_f32_16x16x32_f16 v[102:105], v[164:167], v[204:207], v[102:105]
	v_mfma_f32_16x16x32_f16 v[94:97], v[168:171], v[204:207], v[94:97]
	v_mfma_f32_16x16x32_f16 v[86:89], v[164:167], v[216:219], v[86:89]
	v_mfma_f32_16x16x32_f16 v[78:81], v[168:171], v[216:219], v[78:81]
	v_mfma_f32_16x16x32_f16 v[66:69], v[164:167], v[220:223], v[66:69]
	v_mfma_f32_16x16x32_f16 v[58:61], v[168:171], v[220:223], v[58:61]
	v_mfma_f32_16x16x32_f16 v[118:121], v[172:175], v[208:211], v[118:121]
	v_mfma_f32_16x16x32_f16 v[110:113], v[176:179], v[208:211], v[110:113]
	v_mfma_f32_16x16x32_f16 v[102:105], v[172:175], v[212:215], v[102:105]
	v_mfma_f32_16x16x32_f16 v[94:97], v[176:179], v[212:215], v[94:97]
	v_mfma_f32_16x16x32_f16 v[86:89], v[172:175], v[224:227], v[86:89]
	v_mfma_f32_16x16x32_f16 v[78:81], v[176:179], v[224:227], v[78:81]
	v_mfma_f32_16x16x32_f16 v[66:69], v[172:175], v[228:231], v[66:69]
	v_mfma_f32_16x16x32_f16 v[58:61], v[176:179], v[228:231], v[58:61]
	v_mfma_f32_16x16x32_f16 v[126:129], v[180:183], v[196:199], v[126:129]
	v_mfma_f32_16x16x32_f16 v[122:125], v[184:187], v[196:199], v[122:125]
	v_mfma_f32_16x16x32_f16 v[114:117], v[180:183], v[204:207], v[114:117]
	v_mfma_f32_16x16x32_f16 v[106:109], v[184:187], v[204:207], v[106:109]
	v_mfma_f32_16x16x32_f16 v[98:101], v[180:183], v[216:219], v[98:101]
	v_mfma_f32_16x16x32_f16 v[90:93], v[184:187], v[216:219], v[90:93]
	v_mfma_f32_16x16x32_f16 v[82:85], v[180:183], v[220:223], v[82:85]
	v_mfma_f32_16x16x32_f16 v[74:77], v[184:187], v[220:223], v[74:77]
	v_mfma_f32_16x16x32_f16 v[126:129], v[188:191], v[208:211], v[126:129]
	v_mfma_f32_16x16x32_f16 v[122:125], v[192:195], v[208:211], v[122:125]
	v_mfma_f32_16x16x32_f16 v[114:117], v[188:191], v[212:215], v[114:117]
	v_mfma_f32_16x16x32_f16 v[106:109], v[192:195], v[212:215], v[106:109]
	v_mfma_f32_16x16x32_f16 v[98:101], v[188:191], v[224:227], v[98:101]
	v_mfma_f32_16x16x32_f16 v[90:93], v[192:195], v[224:227], v[90:93]
	v_mfma_f32_16x16x32_f16 v[82:85], v[188:191], v[228:231], v[82:85]
	v_mfma_f32_16x16x32_f16 v[74:77], v[192:195], v[228:231], v[74:77]
	s_barrier
	s_mov_b32 m0, s35
	s_nop 0
	buffer_load_dwordx4 v154, s[8:11], s65 offen lds
	s_mov_b32 m0, s36
	s_add_i32 s62, s62, 0x80080
	buffer_load_dwordx4 v156, s[8:11], s65 offen lds
	s_mov_b32 m0, s39
	s_nop 0
	buffer_load_dwordx4 v154, s[8:11], s62 offen lds
	s_mov_b32 m0, s40
	s_nop 0
	buffer_load_dwordx4 v156, s[8:11], s62 offen lds
	s_mov_b32 m0, s37
	s_nop 0
	buffer_load_dwordx4 v153, s[48:51], s64 offen lds
	s_mov_b32 m0, s38
	s_nop 0
	buffer_load_dwordx4 v155, s[48:51], s64 offen lds
	ds_read_b128 v[196:199], v161 offset:49152
	ds_read_b128 v[204:207], v161 offset:51200
	ds_read_b128 v[208:211], v162 offset:49152
	ds_read_b128 v[212:215], v162 offset:51200
	ds_read_b128 v[216:219], v161 offset:53248
	ds_read_b128 v[220:223], v161 offset:55296
	ds_read_b128 v[224:227], v162 offset:53248
	ds_read_b128 v[228:231], v162 offset:55296
	s_waitcnt vmcnt(8)
	s_waitcnt lgkmcnt(0)
	s_barrier
	s_waitcnt lgkmcnt(0)
	v_mfma_f32_16x16x32_f16 v[54:57], v[164:167], v[196:199], v[54:57]
	v_mfma_f32_16x16x32_f16 v[46:49], v[168:171], v[196:199], v[46:49]
	v_mfma_f32_16x16x32_f16 v[38:41], v[164:167], v[204:207], v[38:41]
	v_mfma_f32_16x16x32_f16 v[30:33], v[168:171], v[204:207], v[30:33]
	v_mfma_f32_16x16x32_f16 v[22:25], v[164:167], v[216:219], v[22:25]
	v_mfma_f32_16x16x32_f16 v[14:17], v[168:171], v[216:219], v[14:17]
	v_mfma_f32_16x16x32_f16 v[6:9], v[164:167], v[220:223], v[6:9]
	v_mfma_f32_16x16x32_f16 v[2:5], v[168:171], v[220:223], v[2:5]
	v_mfma_f32_16x16x32_f16 v[54:57], v[172:175], v[208:211], v[54:57]
	v_mfma_f32_16x16x32_f16 v[46:49], v[176:179], v[208:211], v[46:49]
	v_mfma_f32_16x16x32_f16 v[38:41], v[172:175], v[212:215], v[38:41]
	v_mfma_f32_16x16x32_f16 v[30:33], v[176:179], v[212:215], v[30:33]
	v_mfma_f32_16x16x32_f16 v[22:25], v[172:175], v[224:227], v[22:25]
	v_mfma_f32_16x16x32_f16 v[14:17], v[176:179], v[224:227], v[14:17]
	v_mfma_f32_16x16x32_f16 v[6:9], v[172:175], v[228:231], v[6:9]
	v_mfma_f32_16x16x32_f16 v[2:5], v[176:179], v[228:231], v[2:5]
	v_mfma_f32_16x16x32_f16 v[70:73], v[180:183], v[196:199], v[70:73]
	v_mfma_f32_16x16x32_f16 v[62:65], v[184:187], v[196:199], v[62:65]
	v_mfma_f32_16x16x32_f16 v[50:53], v[180:183], v[204:207], v[50:53]
	v_mfma_f32_16x16x32_f16 v[42:45], v[184:187], v[204:207], v[42:45]
	v_mfma_f32_16x16x32_f16 v[34:37], v[180:183], v[216:219], v[34:37]
	v_mfma_f32_16x16x32_f16 v[26:29], v[184:187], v[216:219], v[26:29]
	v_mfma_f32_16x16x32_f16 v[18:21], v[180:183], v[220:223], v[18:21]
	v_mfma_f32_16x16x32_f16 v[10:13], v[184:187], v[220:223], v[10:13]
	v_mfma_f32_16x16x32_f16 v[70:73], v[188:191], v[208:211], v[70:73]
	v_mfma_f32_16x16x32_f16 v[62:65], v[192:195], v[208:211], v[62:65]
	v_mfma_f32_16x16x32_f16 v[50:53], v[188:191], v[212:215], v[50:53]
	v_mfma_f32_16x16x32_f16 v[42:45], v[192:195], v[212:215], v[42:45]
	v_mfma_f32_16x16x32_f16 v[34:37], v[188:191], v[224:227], v[34:37]
	v_mfma_f32_16x16x32_f16 v[26:29], v[192:195], v[224:227], v[26:29]
	v_mfma_f32_16x16x32_f16 v[18:21], v[188:191], v[228:231], v[18:21]
	v_mfma_f32_16x16x32_f16 v[10:13], v[192:195], v[228:231], v[10:13]
	s_barrier

.Lc0b_first:
	s_add_i32 s55, s52, 0xfff80080
	s_and_b64 s[10:11], s[10:11], exec
	s_cselect_b32 s60, s46, s55
	s_cselect_b32 s55, s47, s53
	s_add_i32 s10, 0, 0x10000
	v_add_u32_e32 v0, s10, v157
	v_add_u32_e32 v147, s10, v158
	s_add_i32 s10, 0, 0x14000
	s_mov_b32 m0, s37
	s_nop 0
	buffer_load_dwordx4 v151, s[48:51], s52 offen lds
	s_mov_b32 m0, s38
	s_nop 0
	buffer_load_dwordx4 v155, s[48:51], s52 offen lds
	ds_read_b128 v[164:167], v0
	ds_read_b128 v[168:171], v0 offset:2048
	ds_read_b128 v[172:175], v147
	ds_read_b128 v[176:179], v147 offset:2048
	v_add_u32_e32 v0, s10, v157
	v_add_u32_e32 v147, s10, v158
	ds_read_b128 v[180:183], v0
	ds_read_b128 v[184:187], v0 offset:2048
	ds_read_b128 v[188:191], v147
	ds_read_b128 v[192:195], v147 offset:2048
	s_or_b32 s56, s60, 0x80
	s_or_b32 s58, s55, 0x80
	ds_read_b128 v[196:199], v161
	ds_read_b128 v[204:207], v161 offset:2048
	ds_read_b128 v[208:211], v162
	ds_read_b128 v[212:215], v162 offset:2048
	ds_read_b128 v[216:219], v161 offset:4096
	ds_read_b128 v[220:223], v161 offset:6144
	ds_read_b128 v[224:227], v162 offset:4096
	ds_read_b128 v[228:231], v162 offset:6144
	s_waitcnt vmcnt(8)
	s_waitcnt lgkmcnt(0)
	s_barrier
	s_waitcnt lgkmcnt(0)
	v_mfma_f32_16x16x32_f16 v[94:97], v[164:167], v[196:199], 0
	v_mfma_f32_16x16x32_f16 v[98:101], v[168:171], v[196:199], 0
	v_mfma_f32_16x16x32_f16 v[62:65], v[164:167], v[204:207], 0
	v_mfma_f32_16x16x32_f16 v[74:77], v[168:171], v[204:207], 0
	v_mfma_f32_16x16x32_f16 v[34:37], v[164:167], v[216:219], 0
	v_mfma_f32_16x16x32_f16 v[42:45], v[168:171], v[216:219], 0
	v_mfma_f32_16x16x32_f16 v[14:17], v[164:167], v[220:223], 0
	v_mfma_f32_16x16x32_f16 v[22:25], v[168:171], v[220:223], 0
	v_mfma_f32_16x16x32_f16 v[94:97], v[172:175], v[208:211], v[94:97]
	v_mfma_f32_16x16x32_f16 v[98:101], v[176:179], v[208:211], v[98:101]
	v_mfma_f32_16x16x32_f16 v[62:65], v[172:175], v[212:215], v[62:65]
	v_mfma_f32_16x16x32_f16 v[74:77], v[176:179], v[212:215], v[74:77]
	v_mfma_f32_16x16x32_f16 v[34:37], v[172:175], v[224:227], v[34:37]
	v_mfma_f32_16x16x32_f16 v[42:45], v[176:179], v[224:227], v[42:45]
	v_mfma_f32_16x16x32_f16 v[14:17], v[172:175], v[228:231], v[14:17]
	v_mfma_f32_16x16x32_f16 v[22:25], v[176:179], v[228:231], v[22:25]
	v_mfma_f32_16x16x32_f16 v[122:125], v[180:183], v[196:199], 0
	v_mfma_f32_16x16x32_f16 v[126:129], v[184:187], v[196:199], 0
	v_mfma_f32_16x16x32_f16 v[110:113], v[180:183], v[204:207], 0
	v_mfma_f32_16x16x32_f16 v[118:121], v[184:187], v[204:207], 0
	v_mfma_f32_16x16x32_f16 v[86:89], v[180:183], v[216:219], 0
	v_mfma_f32_16x16x32_f16 v[102:105], v[184:187], v[216:219], 0
	v_mfma_f32_16x16x32_f16 v[70:73], v[180:183], v[220:223], 0
	v_mfma_f32_16x16x32_f16 v[78:81], v[184:187], v[220:223], 0
	v_mfma_f32_16x16x32_f16 v[122:125], v[188:191], v[208:211], v[122:125]
	v_mfma_f32_16x16x32_f16 v[126:129], v[192:195], v[208:211], v[126:129]
	v_mfma_f32_16x16x32_f16 v[110:113], v[188:191], v[212:215], v[110:113]
	v_mfma_f32_16x16x32_f16 v[118:121], v[192:195], v[212:215], v[118:121]
	v_mfma_f32_16x16x32_f16 v[86:89], v[188:191], v[224:227], v[86:89]
	v_mfma_f32_16x16x32_f16 v[102:105], v[192:195], v[224:227], v[102:105]
	v_mfma_f32_16x16x32_f16 v[70:73], v[188:191], v[228:231], v[70:73]
	v_mfma_f32_16x16x32_f16 v[78:81], v[192:195], v[228:231], v[78:81]
	s_barrier
	s_mov_b32 s10, s50
	s_mov_b32 s11, s51
	s_mov_b32 m0, s2
	s_nop 0
	buffer_load_dwordx4 v153, s[8:11], s55 offen lds
	s_mov_b32 m0, s3
	s_add_i32 s61, s55, 0x80000
	buffer_load_dwordx4 v156, s[8:11], s55 offen lds
	s_mov_b32 m0, s20
	s_nop 0
	buffer_load_dwordx4 v153, s[8:11], s61 offen lds
	s_mov_b32 m0, s21
	s_nop 0
	buffer_load_dwordx4 v156, s[8:11], s61 offen lds
	s_mov_b32 m0, s1
	s_nop 0
	buffer_load_dwordx4 v151, s[48:51], s60 offen lds
	s_mov_b32 m0, s26
	s_nop 0
	buffer_load_dwordx4 v155, s[48:51], s60 offen lds
	ds_read_b128 v[196:199], v161 offset:16384
	ds_read_b128 v[204:207], v161 offset:18432
	ds_read_b128 v[208:211], v162 offset:16384
	ds_read_b128 v[212:215], v162 offset:18432
	ds_read_b128 v[216:219], v161 offset:20480
	ds_read_b128 v[220:223], v161 offset:22528
	ds_read_b128 v[224:227], v162 offset:20480
	ds_read_b128 v[228:231], v162 offset:22528
	s_waitcnt vmcnt(8)
	s_waitcnt lgkmcnt(0)
	s_barrier
	s_waitcnt lgkmcnt(0)
	v_mfma_f32_16x16x32_f16 v[54:57], v[164:167], v[196:199], 0
	v_mfma_f32_16x16x32_f16 v[66:69], v[168:171], v[196:199], 0
	v_mfma_f32_16x16x32_f16 v[30:33], v[164:167], v[204:207], 0
	v_mfma_f32_16x16x32_f16 v[38:41], v[168:171], v[204:207], 0
	v_mfma_f32_16x16x32_f16 v[10:13], v[164:167], v[216:219], 0
	v_mfma_f32_16x16x32_f16 v[18:21], v[168:171], v[216:219], 0
	v_mfma_f32_16x16x32_f16 v[2:5], v[164:167], v[220:223], 0
	v_mfma_f32_16x16x32_f16 v[6:9], v[168:171], v[220:223], 0
	v_mfma_f32_16x16x32_f16 v[54:57], v[172:175], v[208:211], v[54:57]
	v_mfma_f32_16x16x32_f16 v[66:69], v[176:179], v[208:211], v[66:69]
	v_mfma_f32_16x16x32_f16 v[30:33], v[172:175], v[212:215], v[30:33]
	v_mfma_f32_16x16x32_f16 v[38:41], v[176:179], v[212:215], v[38:41]
	v_mfma_f32_16x16x32_f16 v[10:13], v[172:175], v[224:227], v[10:13]
	v_mfma_f32_16x16x32_f16 v[18:21], v[176:179], v[224:227], v[18:21]
	v_mfma_f32_16x16x32_f16 v[2:5], v[172:175], v[228:231], v[2:5]
	v_mfma_f32_16x16x32_f16 v[6:9], v[176:179], v[228:231], v[6:9]
	v_mfma_f32_16x16x32_f16 v[106:109], v[180:183], v[196:199], 0
	v_mfma_f32_16x16x32_f16 v[114:117], v[184:187], v[196:199], 0
	v_mfma_f32_16x16x32_f16 v[82:85], v[180:183], v[204:207], 0
	v_mfma_f32_16x16x32_f16 v[90:93], v[184:187], v[204:207], 0
	v_mfma_f32_16x16x32_f16 v[46:49], v[180:183], v[216:219], 0
	v_mfma_f32_16x16x32_f16 v[58:61], v[184:187], v[216:219], 0
	v_mfma_f32_16x16x32_f16 v[26:29], v[180:183], v[220:223], 0
	v_mfma_f32_16x16x32_f16 v[50:53], v[184:187], v[220:223], 0
	v_mfma_f32_16x16x32_f16 v[106:109], v[188:191], v[208:211], v[106:109]
	v_mfma_f32_16x16x32_f16 v[114:117], v[192:195], v[208:211], v[114:117]
	v_mfma_f32_16x16x32_f16 v[82:85], v[188:191], v[212:215], v[82:85]
	v_mfma_f32_16x16x32_f16 v[90:93], v[192:195], v[212:215], v[90:93]
	v_mfma_f32_16x16x32_f16 v[46:49], v[188:191], v[224:227], v[46:49]
	v_mfma_f32_16x16x32_f16 v[58:61], v[192:195], v[224:227], v[58:61]
	v_mfma_f32_16x16x32_f16 v[26:29], v[188:191], v[228:231], v[26:29]
	v_mfma_f32_16x16x32_f16 v[50:53], v[192:195], v[228:231], v[50:53]
	s_barrier
	s_add_i32 s61, 0, 0x18000
	v_add_u32_e32 v0, s61, v157
	v_add_u32_e32 v147, s61, v158
	s_add_i32 s61, 0, 0x1c000
	s_add_i32 s60, s60, 0x80000
	s_mov_b32 m0, s27
	s_nop 0
	buffer_load_dwordx4 v151, s[48:51], s60 offen lds
	s_mov_b32 m0, s28
	s_nop 0
	buffer_load_dwordx4 v155, s[48:51], s60 offen lds
	ds_read_b128 v[164:167], v0
	ds_read_b128 v[168:171], v0 offset:2048
	ds_read_b128 v[172:175], v147
	ds_read_b128 v[176:179], v147 offset:2048
	v_add_u32_e32 v0, s61, v157
	v_add_u32_e32 v147, s61, v158
	ds_read_b128 v[180:183], v0
	ds_read_b128 v[184:187], v0 offset:2048
	ds_read_b128 v[188:191], v147
	ds_read_b128 v[192:195], v147 offset:2048
	ds_read_b128 v[196:199], v161 offset:32768
	ds_read_b128 v[204:207], v161 offset:34816
	ds_read_b128 v[208:211], v162 offset:32768
	ds_read_b128 v[212:215], v162 offset:34816
	ds_read_b128 v[216:219], v161 offset:36864
	ds_read_b128 v[220:223], v161 offset:38912
	ds_read_b128 v[224:227], v162 offset:36864
	ds_read_b128 v[228:231], v162 offset:38912
	s_waitcnt vmcnt(8)
	s_waitcnt lgkmcnt(0)
	s_barrier
	s_waitcnt lgkmcnt(0)
	v_mfma_f32_16x16x32_f16 v[94:97], v[164:167], v[196:199], v[94:97]
	v_mfma_f32_16x16x32_f16 v[98:101], v[168:171], v[196:199], v[98:101]
	v_mfma_f32_16x16x32_f16 v[62:65], v[164:167], v[204:207], v[62:65]
	v_mfma_f32_16x16x32_f16 v[74:77], v[168:171], v[204:207], v[74:77]
	v_mfma_f32_16x16x32_f16 v[34:37], v[164:167], v[216:219], v[34:37]
	v_mfma_f32_16x16x32_f16 v[42:45], v[168:171], v[216:219], v[42:45]
	v_mfma_f32_16x16x32_f16 v[14:17], v[164:167], v[220:223], v[14:17]
	v_mfma_f32_16x16x32_f16 v[22:25], v[168:171], v[220:223], v[22:25]
	v_mfma_f32_16x16x32_f16 v[94:97], v[172:175], v[208:211], v[94:97]
	v_mfma_f32_16x16x32_f16 v[98:101], v[176:179], v[208:211], v[98:101]
	v_mfma_f32_16x16x32_f16 v[62:65], v[172:175], v[212:215], v[62:65]
	v_mfma_f32_16x16x32_f16 v[74:77], v[176:179], v[212:215], v[74:77]
	v_mfma_f32_16x16x32_f16 v[34:37], v[172:175], v[224:227], v[34:37]
	v_mfma_f32_16x16x32_f16 v[42:45], v[176:179], v[224:227], v[42:45]
	v_mfma_f32_16x16x32_f16 v[14:17], v[172:175], v[228:231], v[14:17]
	v_mfma_f32_16x16x32_f16 v[22:25], v[176:179], v[228:231], v[22:25]
	v_mfma_f32_16x16x32_f16 v[122:125], v[180:183], v[196:199], v[122:125]
	v_mfma_f32_16x16x32_f16 v[126:129], v[184:187], v[196:199], v[126:129]
	v_mfma_f32_16x16x32_f16 v[110:113], v[180:183], v[204:207], v[110:113]
	v_mfma_f32_16x16x32_f16 v[118:121], v[184:187], v[204:207], v[118:121]
	v_mfma_f32_16x16x32_f16 v[86:89], v[180:183], v[216:219], v[86:89]
	v_mfma_f32_16x16x32_f16 v[102:105], v[184:187], v[216:219], v[102:105]
	v_mfma_f32_16x16x32_f16 v[70:73], v[180:183], v[220:223], v[70:73]
	v_mfma_f32_16x16x32_f16 v[78:81], v[184:187], v[220:223], v[78:81]
	v_mfma_f32_16x16x32_f16 v[122:125], v[188:191], v[208:211], v[122:125]
	v_mfma_f32_16x16x32_f16 v[126:129], v[192:195], v[208:211], v[126:129]
	v_mfma_f32_16x16x32_f16 v[110:113], v[188:191], v[212:215], v[110:113]
	v_mfma_f32_16x16x32_f16 v[118:121], v[192:195], v[212:215], v[118:121]
	v_mfma_f32_16x16x32_f16 v[86:89], v[188:191], v[224:227], v[86:89]
	v_mfma_f32_16x16x32_f16 v[102:105], v[192:195], v[224:227], v[102:105]
	v_mfma_f32_16x16x32_f16 v[70:73], v[188:191], v[228:231], v[70:73]
	v_mfma_f32_16x16x32_f16 v[78:81], v[192:195], v[228:231], v[78:81]
	s_barrier
	s_mov_b32 m0, s29
	s_nop 0
	buffer_load_dwordx4 v153, s[8:11], s58 offen lds
	s_mov_b32 m0, s30
	s_add_i32 s55, s55, 0x80080
	buffer_load_dwordx4 v156, s[8:11], s58 offen lds
	s_mov_b32 m0, s35
	s_nop 0
	buffer_load_dwordx4 v153, s[8:11], s55 offen lds
	s_mov_b32 m0, s36
	s_nop 0
	buffer_load_dwordx4 v156, s[8:11], s55 offen lds
	s_mov_b32 m0, s31
	s_nop 0
	buffer_load_dwordx4 v151, s[48:51], s56 offen lds
	s_mov_b32 m0, s34
	s_nop 0
	buffer_load_dwordx4 v155, s[48:51], s56 offen lds
	ds_read_b128 v[196:199], v161 offset:49152
	ds_read_b128 v[204:207], v161 offset:51200
	ds_read_b128 v[208:211], v162 offset:49152
	ds_read_b128 v[212:215], v162 offset:51200
	ds_read_b128 v[216:219], v161 offset:53248
	ds_read_b128 v[220:223], v161 offset:55296
	ds_read_b128 v[224:227], v162 offset:53248
	ds_read_b128 v[228:231], v162 offset:55296
	s_waitcnt vmcnt(8)
	s_waitcnt lgkmcnt(0)
	s_barrier
	s_waitcnt lgkmcnt(0)
	v_mfma_f32_16x16x32_f16 v[54:57], v[164:167], v[196:199], v[54:57]
	v_mfma_f32_16x16x32_f16 v[66:69], v[168:171], v[196:199], v[66:69]
	v_mfma_f32_16x16x32_f16 v[30:33], v[164:167], v[204:207], v[30:33]
	v_mfma_f32_16x16x32_f16 v[38:41], v[168:171], v[204:207], v[38:41]
	v_mfma_f32_16x16x32_f16 v[10:13], v[164:167], v[216:219], v[10:13]
	v_mfma_f32_16x16x32_f16 v[18:21], v[168:171], v[216:219], v[18:21]
	v_mfma_f32_16x16x32_f16 v[2:5], v[164:167], v[220:223], v[2:5]
	v_mfma_f32_16x16x32_f16 v[6:9], v[168:171], v[220:223], v[6:9]
	v_mfma_f32_16x16x32_f16 v[54:57], v[172:175], v[208:211], v[54:57]
	v_mfma_f32_16x16x32_f16 v[66:69], v[176:179], v[208:211], v[66:69]
	v_mfma_f32_16x16x32_f16 v[30:33], v[172:175], v[212:215], v[30:33]
	v_mfma_f32_16x16x32_f16 v[38:41], v[176:179], v[212:215], v[38:41]
	v_mfma_f32_16x16x32_f16 v[10:13], v[172:175], v[224:227], v[10:13]
	v_mfma_f32_16x16x32_f16 v[18:21], v[176:179], v[224:227], v[18:21]
	v_mfma_f32_16x16x32_f16 v[2:5], v[172:175], v[228:231], v[2:5]
	v_mfma_f32_16x16x32_f16 v[6:9], v[176:179], v[228:231], v[6:9]
	v_mfma_f32_16x16x32_f16 v[106:109], v[180:183], v[196:199], v[106:109]
	v_mfma_f32_16x16x32_f16 v[114:117], v[184:187], v[196:199], v[114:117]
	v_mfma_f32_16x16x32_f16 v[82:85], v[180:183], v[204:207], v[82:85]
	v_mfma_f32_16x16x32_f16 v[90:93], v[184:187], v[204:207], v[90:93]
	v_mfma_f32_16x16x32_f16 v[46:49], v[180:183], v[216:219], v[46:49]
	v_mfma_f32_16x16x32_f16 v[58:61], v[184:187], v[216:219], v[58:61]
	v_mfma_f32_16x16x32_f16 v[26:29], v[180:183], v[220:223], v[26:29]
	v_mfma_f32_16x16x32_f16 v[50:53], v[184:187], v[220:223], v[50:53]
	v_mfma_f32_16x16x32_f16 v[106:109], v[188:191], v[208:211], v[106:109]
	v_mfma_f32_16x16x32_f16 v[114:117], v[192:195], v[208:211], v[114:117]
	v_mfma_f32_16x16x32_f16 v[82:85], v[188:191], v[212:215], v[82:85]
	v_mfma_f32_16x16x32_f16 v[90:93], v[192:195], v[212:215], v[90:93]
	v_mfma_f32_16x16x32_f16 v[46:49], v[188:191], v[224:227], v[46:49]
	v_mfma_f32_16x16x32_f16 v[58:61], v[192:195], v[224:227], v[58:61]
	v_mfma_f32_16x16x32_f16 v[26:29], v[188:191], v[228:231], v[26:29]
	v_mfma_f32_16x16x32_f16 v[50:53], v[192:195], v[228:231], v[50:53]
	s_barrier
	s_branch .Lc0b_tail
.Lc0b_final:
	s_add_i32 s55, s52, 0xfff80080
	s_and_b64 s[10:11], s[10:11], exec
	s_cselect_b32 s60, s46, s55
	s_cselect_b32 s55, s47, s53
	s_add_i32 s10, 0, 0x10000
	v_add_u32_e32 v0, s10, v157
	v_add_u32_e32 v147, s10, v158
	s_add_i32 s10, 0, 0x14000
	s_mov_b32 m0, s37
	s_nop 0
	buffer_load_dwordx4 v151, s[48:51], s52 offen lds
	s_mov_b32 m0, s38
	s_nop 0
	buffer_load_dwordx4 v155, s[48:51], s52 offen lds
	ds_read_b128 v[164:167], v0
	ds_read_b128 v[168:171], v0 offset:2048
	ds_read_b128 v[172:175], v147
	ds_read_b128 v[176:179], v147 offset:2048
	v_add_u32_e32 v0, s10, v157
	v_add_u32_e32 v147, s10, v158
	ds_read_b128 v[180:183], v0
	ds_read_b128 v[184:187], v0 offset:2048
	ds_read_b128 v[188:191], v147
	ds_read_b128 v[192:195], v147 offset:2048
	s_or_b32 s56, s60, 0x80
	s_or_b32 s58, s55, 0x80
	ds_read_b128 v[196:199], v161
	ds_read_b128 v[204:207], v161 offset:2048
	ds_read_b128 v[208:211], v162
	ds_read_b128 v[212:215], v162 offset:2048
	ds_read_b128 v[216:219], v161 offset:4096
	ds_read_b128 v[220:223], v161 offset:6144
	ds_read_b128 v[224:227], v162 offset:4096
	ds_read_b128 v[228:231], v162 offset:6144
	s_waitcnt vmcnt(8)
	s_waitcnt lgkmcnt(0)
	s_barrier
	s_waitcnt lgkmcnt(0)
	v_mfma_f32_16x16x32_f16 v[94:97], v[164:167], v[196:199], v[94:97]
	v_mfma_f32_16x16x32_f16 v[98:101], v[168:171], v[196:199], v[98:101]
	v_mfma_f32_16x16x32_f16 v[62:65], v[164:167], v[204:207], v[62:65]
	v_mfma_f32_16x16x32_f16 v[74:77], v[168:171], v[204:207], v[74:77]
	v_mfma_f32_16x16x32_f16 v[34:37], v[164:167], v[216:219], v[34:37]
	v_mfma_f32_16x16x32_f16 v[42:45], v[168:171], v[216:219], v[42:45]
	v_mfma_f32_16x16x32_f16 v[14:17], v[164:167], v[220:223], v[14:17]
	v_mfma_f32_16x16x32_f16 v[22:25], v[168:171], v[220:223], v[22:25]
	v_mfma_f32_16x16x32_f16 v[94:97], v[172:175], v[208:211], v[94:97]
	v_mfma_f32_16x16x32_f16 v[98:101], v[176:179], v[208:211], v[98:101]
	v_mfma_f32_16x16x32_f16 v[62:65], v[172:175], v[212:215], v[62:65]
	v_mfma_f32_16x16x32_f16 v[74:77], v[176:179], v[212:215], v[74:77]
	v_mfma_f32_16x16x32_f16 v[34:37], v[172:175], v[224:227], v[34:37]
	v_mfma_f32_16x16x32_f16 v[42:45], v[176:179], v[224:227], v[42:45]
	v_mfma_f32_16x16x32_f16 v[14:17], v[172:175], v[228:231], v[14:17]
	v_mfma_f32_16x16x32_f16 v[22:25], v[176:179], v[228:231], v[22:25]
	v_mfma_f32_16x16x32_f16 v[122:125], v[180:183], v[196:199], v[122:125]
	v_mfma_f32_16x16x32_f16 v[126:129], v[184:187], v[196:199], v[126:129]
	v_mfma_f32_16x16x32_f16 v[110:113], v[180:183], v[204:207], v[110:113]
	v_mfma_f32_16x16x32_f16 v[118:121], v[184:187], v[204:207], v[118:121]
	v_mfma_f32_16x16x32_f16 v[86:89], v[180:183], v[216:219], v[86:89]
	v_mfma_f32_16x16x32_f16 v[102:105], v[184:187], v[216:219], v[102:105]
	v_mfma_f32_16x16x32_f16 v[70:73], v[180:183], v[220:223], v[70:73]
	v_mfma_f32_16x16x32_f16 v[78:81], v[184:187], v[220:223], v[78:81]
	v_mfma_f32_16x16x32_f16 v[122:125], v[188:191], v[208:211], v[122:125]
	v_mfma_f32_16x16x32_f16 v[126:129], v[192:195], v[208:211], v[126:129]
	v_mfma_f32_16x16x32_f16 v[110:113], v[188:191], v[212:215], v[110:113]
	v_mfma_f32_16x16x32_f16 v[118:121], v[192:195], v[212:215], v[118:121]
	v_mfma_f32_16x16x32_f16 v[86:89], v[188:191], v[224:227], v[86:89]
	v_mfma_f32_16x16x32_f16 v[102:105], v[192:195], v[224:227], v[102:105]
	v_mfma_f32_16x16x32_f16 v[70:73], v[188:191], v[228:231], v[70:73]
	v_mfma_f32_16x16x32_f16 v[78:81], v[192:195], v[228:231], v[78:81]
	s_barrier
	s_mov_b32 s10, s50
	s_mov_b32 s11, s51
	ds_read_b128 v[196:199], v161 offset:16384
	ds_read_b128 v[204:207], v161 offset:18432
	ds_read_b128 v[208:211], v162 offset:16384
	ds_read_b128 v[212:215], v162 offset:18432
	ds_read_b128 v[216:219], v161 offset:20480
	ds_read_b128 v[220:223], v161 offset:22528
	ds_read_b128 v[224:227], v162 offset:20480
	ds_read_b128 v[228:231], v162 offset:22528
	s_add_i32 s61, s55, 0x80000
	s_waitcnt vmcnt(2)
	s_waitcnt lgkmcnt(0)
	s_barrier
	s_waitcnt lgkmcnt(0)
	v_mfma_f32_16x16x32_f16 v[54:57], v[164:167], v[196:199], v[54:57]
	v_mfma_f32_16x16x32_f16 v[66:69], v[168:171], v[196:199], v[66:69]
	v_mfma_f32_16x16x32_f16 v[30:33], v[164:167], v[204:207], v[30:33]
	v_mfma_f32_16x16x32_f16 v[38:41], v[168:171], v[204:207], v[38:41]
	v_mfma_f32_16x16x32_f16 v[10:13], v[164:167], v[216:219], v[10:13]
	v_mfma_f32_16x16x32_f16 v[18:21], v[168:171], v[216:219], v[18:21]
	v_mfma_f32_16x16x32_f16 v[2:5], v[164:167], v[220:223], v[2:5]
	v_mfma_f32_16x16x32_f16 v[6:9], v[168:171], v[220:223], v[6:9]
	v_mfma_f32_16x16x32_f16 v[54:57], v[172:175], v[208:211], v[54:57]
	v_mfma_f32_16x16x32_f16 v[66:69], v[176:179], v[208:211], v[66:69]
	v_mfma_f32_16x16x32_f16 v[30:33], v[172:175], v[212:215], v[30:33]
	v_mfma_f32_16x16x32_f16 v[38:41], v[176:179], v[212:215], v[38:41]
	v_mfma_f32_16x16x32_f16 v[10:13], v[172:175], v[224:227], v[10:13]
	v_mfma_f32_16x16x32_f16 v[18:21], v[176:179], v[224:227], v[18:21]
	v_mfma_f32_16x16x32_f16 v[2:5], v[172:175], v[228:231], v[2:5]
	v_mfma_f32_16x16x32_f16 v[6:9], v[176:179], v[228:231], v[6:9]
	v_mfma_f32_16x16x32_f16 v[106:109], v[180:183], v[196:199], v[106:109]
	v_mfma_f32_16x16x32_f16 v[114:117], v[184:187], v[196:199], v[114:117]
	v_mfma_f32_16x16x32_f16 v[82:85], v[180:183], v[204:207], v[82:85]
	v_mfma_f32_16x16x32_f16 v[90:93], v[184:187], v[204:207], v[90:93]
	v_mfma_f32_16x16x32_f16 v[46:49], v[180:183], v[216:219], v[46:49]
	v_mfma_f32_16x16x32_f16 v[58:61], v[184:187], v[216:219], v[58:61]
	v_mfma_f32_16x16x32_f16 v[26:29], v[180:183], v[220:223], v[26:29]
	v_mfma_f32_16x16x32_f16 v[50:53], v[184:187], v[220:223], v[50:53]
	v_mfma_f32_16x16x32_f16 v[106:109], v[188:191], v[208:211], v[106:109]
	v_mfma_f32_16x16x32_f16 v[114:117], v[192:195], v[208:211], v[114:117]
	v_mfma_f32_16x16x32_f16 v[82:85], v[188:191], v[212:215], v[82:85]
	v_mfma_f32_16x16x32_f16 v[90:93], v[192:195], v[212:215], v[90:93]
	v_mfma_f32_16x16x32_f16 v[46:49], v[188:191], v[224:227], v[46:49]
	v_mfma_f32_16x16x32_f16 v[58:61], v[192:195], v[224:227], v[58:61]
	v_mfma_f32_16x16x32_f16 v[26:29], v[188:191], v[228:231], v[26:29]
	v_mfma_f32_16x16x32_f16 v[50:53], v[192:195], v[228:231], v[50:53]
	s_barrier
	s_add_i32 s61, 0, 0x18000
	v_add_u32_e32 v0, s61, v157
	v_add_u32_e32 v147, s61, v158
	s_add_i32 s61, 0, 0x1c000
	ds_read_b128 v[164:167], v0
	ds_read_b128 v[168:171], v0 offset:2048
	ds_read_b128 v[172:175], v147
	ds_read_b128 v[176:179], v147 offset:2048
	v_add_u32_e32 v0, s61, v157
	v_add_u32_e32 v147, s61, v158
	ds_read_b128 v[180:183], v0
	ds_read_b128 v[184:187], v0 offset:2048
	ds_read_b128 v[188:191], v147
	ds_read_b128 v[192:195], v147 offset:2048
	s_add_i32 s60, s60, 0x80000
	ds_read_b128 v[196:199], v161 offset:32768
	ds_read_b128 v[204:207], v161 offset:34816
	ds_read_b128 v[208:211], v162 offset:32768
	ds_read_b128 v[212:215], v162 offset:34816
	ds_read_b128 v[216:219], v161 offset:36864
	ds_read_b128 v[220:223], v161 offset:38912
	ds_read_b128 v[224:227], v162 offset:36864
	ds_read_b128 v[228:231], v162 offset:38912
	s_waitcnt vmcnt(0)
	s_waitcnt lgkmcnt(0)
	s_barrier
	s_waitcnt lgkmcnt(0)
	v_mfma_f32_16x16x32_f16 v[94:97], v[164:167], v[196:199], v[94:97]
	v_mfma_f32_16x16x32_f16 v[98:101], v[168:171], v[196:199], v[98:101]
	v_mfma_f32_16x16x32_f16 v[62:65], v[164:167], v[204:207], v[62:65]
	v_mfma_f32_16x16x32_f16 v[74:77], v[168:171], v[204:207], v[74:77]
	v_mfma_f32_16x16x32_f16 v[34:37], v[164:167], v[216:219], v[34:37]
	v_mfma_f32_16x16x32_f16 v[42:45], v[168:171], v[216:219], v[42:45]
	v_mfma_f32_16x16x32_f16 v[14:17], v[164:167], v[220:223], v[14:17]
	v_mfma_f32_16x16x32_f16 v[22:25], v[168:171], v[220:223], v[22:25]
	v_mfma_f32_16x16x32_f16 v[94:97], v[172:175], v[208:211], v[94:97]
	v_mfma_f32_16x16x32_f16 v[98:101], v[176:179], v[208:211], v[98:101]
	v_mfma_f32_16x16x32_f16 v[62:65], v[172:175], v[212:215], v[62:65]
	v_mfma_f32_16x16x32_f16 v[74:77], v[176:179], v[212:215], v[74:77]
	v_mfma_f32_16x16x32_f16 v[34:37], v[172:175], v[224:227], v[34:37]
	v_mfma_f32_16x16x32_f16 v[42:45], v[176:179], v[224:227], v[42:45]
	v_mfma_f32_16x16x32_f16 v[14:17], v[172:175], v[228:231], v[14:17]
	v_mfma_f32_16x16x32_f16 v[22:25], v[176:179], v[228:231], v[22:25]
	v_mfma_f32_16x16x32_f16 v[122:125], v[180:183], v[196:199], v[122:125]
	v_mfma_f32_16x16x32_f16 v[126:129], v[184:187], v[196:199], v[126:129]
	v_mfma_f32_16x16x32_f16 v[110:113], v[180:183], v[204:207], v[110:113]
	v_mfma_f32_16x16x32_f16 v[118:121], v[184:187], v[204:207], v[118:121]
	v_mfma_f32_16x16x32_f16 v[86:89], v[180:183], v[216:219], v[86:89]
	v_mfma_f32_16x16x32_f16 v[102:105], v[184:187], v[216:219], v[102:105]
	v_mfma_f32_16x16x32_f16 v[70:73], v[180:183], v[220:223], v[70:73]
	v_mfma_f32_16x16x32_f16 v[78:81], v[184:187], v[220:223], v[78:81]
	v_mfma_f32_16x16x32_f16 v[122:125], v[188:191], v[208:211], v[122:125]
	v_mfma_f32_16x16x32_f16 v[126:129], v[192:195], v[208:211], v[126:129]
	v_mfma_f32_16x16x32_f16 v[110:113], v[188:191], v[212:215], v[110:113]
	v_mfma_f32_16x16x32_f16 v[118:121], v[192:195], v[212:215], v[118:121]
	v_mfma_f32_16x16x32_f16 v[86:89], v[188:191], v[224:227], v[86:89]
	v_mfma_f32_16x16x32_f16 v[102:105], v[192:195], v[224:227], v[102:105]
	v_mfma_f32_16x16x32_f16 v[70:73], v[188:191], v[228:231], v[70:73]
	v_mfma_f32_16x16x32_f16 v[78:81], v[192:195], v[228:231], v[78:81]
	s_barrier
	ds_read_b128 v[196:199], v161 offset:49152
	ds_read_b128 v[204:207], v161 offset:51200
	ds_read_b128 v[208:211], v162 offset:49152
	ds_read_b128 v[212:215], v162 offset:51200
	ds_read_b128 v[216:219], v161 offset:53248
	ds_read_b128 v[220:223], v161 offset:55296
	ds_read_b128 v[224:227], v162 offset:53248
	ds_read_b128 v[228:231], v162 offset:55296
	s_add_i32 s55, s55, 0x80080
	s_waitcnt vmcnt(0)
	s_waitcnt lgkmcnt(0)
	s_barrier
	s_waitcnt lgkmcnt(0)
	v_mfma_f32_16x16x32_f16 v[54:57], v[164:167], v[196:199], v[54:57]
	v_mfma_f32_16x16x32_f16 v[66:69], v[168:171], v[196:199], v[66:69]
	v_mfma_f32_16x16x32_f16 v[30:33], v[164:167], v[204:207], v[30:33]
	v_mfma_f32_16x16x32_f16 v[38:41], v[168:171], v[204:207], v[38:41]
	v_mfma_f32_16x16x32_f16 v[10:13], v[164:167], v[216:219], v[10:13]
	v_mfma_f32_16x16x32_f16 v[18:21], v[168:171], v[216:219], v[18:21]
	v_mfma_f32_16x16x32_f16 v[2:5], v[164:167], v[220:223], v[2:5]
	v_mfma_f32_16x16x32_f16 v[6:9], v[168:171], v[220:223], v[6:9]
	v_mfma_f32_16x16x32_f16 v[54:57], v[172:175], v[208:211], v[54:57]
	v_mfma_f32_16x16x32_f16 v[66:69], v[176:179], v[208:211], v[66:69]
	v_mfma_f32_16x16x32_f16 v[30:33], v[172:175], v[212:215], v[30:33]
	v_mfma_f32_16x16x32_f16 v[38:41], v[176:179], v[212:215], v[38:41]
	v_mfma_f32_16x16x32_f16 v[10:13], v[172:175], v[224:227], v[10:13]
	v_mfma_f32_16x16x32_f16 v[18:21], v[176:179], v[224:227], v[18:21]
	v_mfma_f32_16x16x32_f16 v[2:5], v[172:175], v[228:231], v[2:5]
	v_mfma_f32_16x16x32_f16 v[6:9], v[176:179], v[228:231], v[6:9]
	v_mfma_f32_16x16x32_f16 v[106:109], v[180:183], v[196:199], v[106:109]
	v_mfma_f32_16x16x32_f16 v[114:117], v[184:187], v[196:199], v[114:117]
	v_mfma_f32_16x16x32_f16 v[82:85], v[180:183], v[204:207], v[82:85]
	v_mfma_f32_16x16x32_f16 v[90:93], v[184:187], v[204:207], v[90:93]
	v_mfma_f32_16x16x32_f16 v[46:49], v[180:183], v[216:219], v[46:49]
	v_mfma_f32_16x16x32_f16 v[58:61], v[184:187], v[216:219], v[58:61]
	v_mfma_f32_16x16x32_f16 v[26:29], v[180:183], v[220:223], v[26:29]
	v_mfma_f32_16x16x32_f16 v[50:53], v[184:187], v[220:223], v[50:53]
	v_mfma_f32_16x16x32_f16 v[106:109], v[188:191], v[208:211], v[106:109]
	v_mfma_f32_16x16x32_f16 v[114:117], v[192:195], v[208:211], v[114:117]
	v_mfma_f32_16x16x32_f16 v[82:85], v[188:191], v[212:215], v[82:85]
	v_mfma_f32_16x16x32_f16 v[90:93], v[192:195], v[212:215], v[90:93]
	v_mfma_f32_16x16x32_f16 v[46:49], v[188:191], v[224:227], v[46:49]
	v_mfma_f32_16x16x32_f16 v[58:61], v[192:195], v[224:227], v[58:61]
	v_mfma_f32_16x16x32_f16 v[26:29], v[188:191], v[228:231], v[26:29]
	v_mfma_f32_16x16x32_f16 v[50:53], v[192:195], v[228:231], v[50:53]
	s_barrier
	s_branch .Lc0b_tail

.Lc0b_norm:
	s_add_i32 s55, s52, 0xfff80080
	s_and_b64 s[10:11], s[10:11], exec
	s_cselect_b32 s60, s46, s55
	s_cselect_b32 s55, s47, s53
	s_add_i32 s10, 0, 0x10000
	v_add_u32_e32 v0, s10, v157
	v_add_u32_e32 v147, s10, v158
	s_add_i32 s10, 0, 0x14000
	s_mov_b32 m0, s37
	s_nop 0
	buffer_load_dwordx4 v151, s[48:51], s52 offen lds
	s_mov_b32 m0, s38
	s_nop 0
	buffer_load_dwordx4 v155, s[48:51], s52 offen lds
	ds_read_b128 v[164:167], v0
	ds_read_b128 v[168:171], v0 offset:2048
	ds_read_b128 v[172:175], v147
	ds_read_b128 v[176:179], v147 offset:2048
	v_add_u32_e32 v0, s10, v157
	v_add_u32_e32 v147, s10, v158
	ds_read_b128 v[180:183], v0
	ds_read_b128 v[184:187], v0 offset:2048
	ds_read_b128 v[188:191], v147
	ds_read_b128 v[192:195], v147 offset:2048
	s_or_b32 s56, s60, 0x80
	s_or_b32 s58, s55, 0x80
	ds_read_b128 v[196:199], v161
	ds_read_b128 v[204:207], v161 offset:2048
	ds_read_b128 v[208:211], v162
	ds_read_b128 v[212:215], v162 offset:2048
	ds_read_b128 v[216:219], v161 offset:4096
	ds_read_b128 v[220:223], v161 offset:6144
	ds_read_b128 v[224:227], v162 offset:4096
	ds_read_b128 v[228:231], v162 offset:6144
	s_waitcnt vmcnt(8)
	s_waitcnt lgkmcnt(0)
	s_barrier
	s_waitcnt lgkmcnt(0)
	v_mfma_f32_16x16x32_f16 v[94:97], v[164:167], v[196:199], v[94:97]
	v_mfma_f32_16x16x32_f16 v[98:101], v[168:171], v[196:199], v[98:101]
	v_mfma_f32_16x16x32_f16 v[62:65], v[164:167], v[204:207], v[62:65]
	v_mfma_f32_16x16x32_f16 v[74:77], v[168:171], v[204:207], v[74:77]
	v_mfma_f32_16x16x32_f16 v[34:37], v[164:167], v[216:219], v[34:37]
	v_mfma_f32_16x16x32_f16 v[42:45], v[168:171], v[216:219], v[42:45]
	v_mfma_f32_16x16x32_f16 v[14:17], v[164:167], v[220:223], v[14:17]
	v_mfma_f32_16x16x32_f16 v[22:25], v[168:171], v[220:223], v[22:25]
	v_mfma_f32_16x16x32_f16 v[94:97], v[172:175], v[208:211], v[94:97]
	v_mfma_f32_16x16x32_f16 v[98:101], v[176:179], v[208:211], v[98:101]
	v_mfma_f32_16x16x32_f16 v[62:65], v[172:175], v[212:215], v[62:65]
	v_mfma_f32_16x16x32_f16 v[74:77], v[176:179], v[212:215], v[74:77]
	v_mfma_f32_16x16x32_f16 v[34:37], v[172:175], v[224:227], v[34:37]
	v_mfma_f32_16x16x32_f16 v[42:45], v[176:179], v[224:227], v[42:45]
	v_mfma_f32_16x16x32_f16 v[14:17], v[172:175], v[228:231], v[14:17]
	v_mfma_f32_16x16x32_f16 v[22:25], v[176:179], v[228:231], v[22:25]
	v_mfma_f32_16x16x32_f16 v[122:125], v[180:183], v[196:199], v[122:125]
	v_mfma_f32_16x16x32_f16 v[126:129], v[184:187], v[196:199], v[126:129]
	v_mfma_f32_16x16x32_f16 v[110:113], v[180:183], v[204:207], v[110:113]
	v_mfma_f32_16x16x32_f16 v[118:121], v[184:187], v[204:207], v[118:121]
	v_mfma_f32_16x16x32_f16 v[86:89], v[180:183], v[216:219], v[86:89]
	v_mfma_f32_16x16x32_f16 v[102:105], v[184:187], v[216:219], v[102:105]
	v_mfma_f32_16x16x32_f16 v[70:73], v[180:183], v[220:223], v[70:73]
	v_mfma_f32_16x16x32_f16 v[78:81], v[184:187], v[220:223], v[78:81]
	v_mfma_f32_16x16x32_f16 v[122:125], v[188:191], v[208:211], v[122:125]
	v_mfma_f32_16x16x32_f16 v[126:129], v[192:195], v[208:211], v[126:129]
	v_mfma_f32_16x16x32_f16 v[110:113], v[188:191], v[212:215], v[110:113]
	v_mfma_f32_16x16x32_f16 v[118:121], v[192:195], v[212:215], v[118:121]
	v_mfma_f32_16x16x32_f16 v[86:89], v[188:191], v[224:227], v[86:89]
	v_mfma_f32_16x16x32_f16 v[102:105], v[192:195], v[224:227], v[102:105]
	v_mfma_f32_16x16x32_f16 v[70:73], v[188:191], v[228:231], v[70:73]
	v_mfma_f32_16x16x32_f16 v[78:81], v[192:195], v[228:231], v[78:81]
	s_barrier
	s_mov_b32 s10, s50
	s_mov_b32 s11, s51
	s_mov_b32 m0, s2
	s_nop 0
	buffer_load_dwordx4 v153, s[8:11], s55 offen lds
	s_mov_b32 m0, s3
	s_add_i32 s61, s55, 0x80000
	buffer_load_dwordx4 v156, s[8:11], s55 offen lds
	s_mov_b32 m0, s20
	s_nop 0
	buffer_load_dwordx4 v153, s[8:11], s61 offen lds
	s_mov_b32 m0, s21
	s_nop 0
	buffer_load_dwordx4 v156, s[8:11], s61 offen lds
	s_mov_b32 m0, s1
	s_nop 0
	buffer_load_dwordx4 v151, s[48:51], s60 offen lds
	s_mov_b32 m0, s26
	s_nop 0
	buffer_load_dwordx4 v155, s[48:51], s60 offen lds
	ds_read_b128 v[196:199], v161 offset:16384
	ds_read_b128 v[204:207], v161 offset:18432
	ds_read_b128 v[208:211], v162 offset:16384
	ds_read_b128 v[212:215], v162 offset:18432
	ds_read_b128 v[216:219], v161 offset:20480
	ds_read_b128 v[220:223], v161 offset:22528
	ds_read_b128 v[224:227], v162 offset:20480
	ds_read_b128 v[228:231], v162 offset:22528
	s_waitcnt vmcnt(8)
	s_waitcnt lgkmcnt(0)
	s_barrier
	s_waitcnt lgkmcnt(0)
	v_mfma_f32_16x16x32_f16 v[54:57], v[164:167], v[196:199], v[54:57]
	v_mfma_f32_16x16x32_f16 v[66:69], v[168:171], v[196:199], v[66:69]
	v_mfma_f32_16x16x32_f16 v[30:33], v[164:167], v[204:207], v[30:33]
	v_mfma_f32_16x16x32_f16 v[38:41], v[168:171], v[204:207], v[38:41]
	v_mfma_f32_16x16x32_f16 v[10:13], v[164:167], v[216:219], v[10:13]
	v_mfma_f32_16x16x32_f16 v[18:21], v[168:171], v[216:219], v[18:21]
	v_mfma_f32_16x16x32_f16 v[2:5], v[164:167], v[220:223], v[2:5]
	v_mfma_f32_16x16x32_f16 v[6:9], v[168:171], v[220:223], v[6:9]
	v_mfma_f32_16x16x32_f16 v[54:57], v[172:175], v[208:211], v[54:57]
	v_mfma_f32_16x16x32_f16 v[66:69], v[176:179], v[208:211], v[66:69]
	v_mfma_f32_16x16x32_f16 v[30:33], v[172:175], v[212:215], v[30:33]
	v_mfma_f32_16x16x32_f16 v[38:41], v[176:179], v[212:215], v[38:41]
	v_mfma_f32_16x16x32_f16 v[10:13], v[172:175], v[224:227], v[10:13]
	v_mfma_f32_16x16x32_f16 v[18:21], v[176:179], v[224:227], v[18:21]
	v_mfma_f32_16x16x32_f16 v[2:5], v[172:175], v[228:231], v[2:5]
	v_mfma_f32_16x16x32_f16 v[6:9], v[176:179], v[228:231], v[6:9]
	v_mfma_f32_16x16x32_f16 v[106:109], v[180:183], v[196:199], v[106:109]
	v_mfma_f32_16x16x32_f16 v[114:117], v[184:187], v[196:199], v[114:117]
	v_mfma_f32_16x16x32_f16 v[82:85], v[180:183], v[204:207], v[82:85]
	v_mfma_f32_16x16x32_f16 v[90:93], v[184:187], v[204:207], v[90:93]
	v_mfma_f32_16x16x32_f16 v[46:49], v[180:183], v[216:219], v[46:49]
	v_mfma_f32_16x16x32_f16 v[58:61], v[184:187], v[216:219], v[58:61]
	v_mfma_f32_16x16x32_f16 v[26:29], v[180:183], v[220:223], v[26:29]
	v_mfma_f32_16x16x32_f16 v[50:53], v[184:187], v[220:223], v[50:53]
	v_mfma_f32_16x16x32_f16 v[106:109], v[188:191], v[208:211], v[106:109]
	v_mfma_f32_16x16x32_f16 v[114:117], v[192:195], v[208:211], v[114:117]
	v_mfma_f32_16x16x32_f16 v[82:85], v[188:191], v[212:215], v[82:85]
	v_mfma_f32_16x16x32_f16 v[90:93], v[192:195], v[212:215], v[90:93]
	v_mfma_f32_16x16x32_f16 v[46:49], v[188:191], v[224:227], v[46:49]
	v_mfma_f32_16x16x32_f16 v[58:61], v[192:195], v[224:227], v[58:61]
	v_mfma_f32_16x16x32_f16 v[26:29], v[188:191], v[228:231], v[26:29]
	v_mfma_f32_16x16x32_f16 v[50:53], v[192:195], v[228:231], v[50:53]
	s_barrier
	s_add_i32 s61, 0, 0x18000
	v_add_u32_e32 v0, s61, v157
	v_add_u32_e32 v147, s61, v158
	s_add_i32 s61, 0, 0x1c000
	s_add_i32 s60, s60, 0x80000
	s_mov_b32 m0, s27
	s_nop 0
	buffer_load_dwordx4 v151, s[48:51], s60 offen lds
	s_mov_b32 m0, s28
	s_nop 0
	buffer_load_dwordx4 v155, s[48:51], s60 offen lds
	ds_read_b128 v[164:167], v0
	ds_read_b128 v[168:171], v0 offset:2048
	ds_read_b128 v[172:175], v147
	ds_read_b128 v[176:179], v147 offset:2048
	v_add_u32_e32 v0, s61, v157
	v_add_u32_e32 v147, s61, v158
	ds_read_b128 v[180:183], v0
	ds_read_b128 v[184:187], v0 offset:2048
	ds_read_b128 v[188:191], v147
	ds_read_b128 v[192:195], v147 offset:2048
	ds_read_b128 v[196:199], v161 offset:32768
	ds_read_b128 v[204:207], v161 offset:34816
	ds_read_b128 v[208:211], v162 offset:32768
	ds_read_b128 v[212:215], v162 offset:34816
	ds_read_b128 v[216:219], v161 offset:36864
	ds_read_b128 v[220:223], v161 offset:38912
	ds_read_b128 v[224:227], v162 offset:36864
	ds_read_b128 v[228:231], v162 offset:38912
	s_waitcnt vmcnt(8)
	s_waitcnt lgkmcnt(0)
	s_barrier
	s_waitcnt lgkmcnt(0)
	v_mfma_f32_16x16x32_f16 v[94:97], v[164:167], v[196:199], v[94:97]
	v_mfma_f32_16x16x32_f16 v[98:101], v[168:171], v[196:199], v[98:101]
	v_mfma_f32_16x16x32_f16 v[62:65], v[164:167], v[204:207], v[62:65]
	v_mfma_f32_16x16x32_f16 v[74:77], v[168:171], v[204:207], v[74:77]
	v_mfma_f32_16x16x32_f16 v[34:37], v[164:167], v[216:219], v[34:37]
	v_mfma_f32_16x16x32_f16 v[42:45], v[168:171], v[216:219], v[42:45]
	v_mfma_f32_16x16x32_f16 v[14:17], v[164:167], v[220:223], v[14:17]
	v_mfma_f32_16x16x32_f16 v[22:25], v[168:171], v[220:223], v[22:25]
	v_mfma_f32_16x16x32_f16 v[94:97], v[172:175], v[208:211], v[94:97]
	v_mfma_f32_16x16x32_f16 v[98:101], v[176:179], v[208:211], v[98:101]
	v_mfma_f32_16x16x32_f16 v[62:65], v[172:175], v[212:215], v[62:65]
	v_mfma_f32_16x16x32_f16 v[74:77], v[176:179], v[212:215], v[74:77]
	v_mfma_f32_16x16x32_f16 v[34:37], v[172:175], v[224:227], v[34:37]
	v_mfma_f32_16x16x32_f16 v[42:45], v[176:179], v[224:227], v[42:45]
	v_mfma_f32_16x16x32_f16 v[14:17], v[172:175], v[228:231], v[14:17]
	v_mfma_f32_16x16x32_f16 v[22:25], v[176:179], v[228:231], v[22:25]
	v_mfma_f32_16x16x32_f16 v[122:125], v[180:183], v[196:199], v[122:125]
	v_mfma_f32_16x16x32_f16 v[126:129], v[184:187], v[196:199], v[126:129]
	v_mfma_f32_16x16x32_f16 v[110:113], v[180:183], v[204:207], v[110:113]
	v_mfma_f32_16x16x32_f16 v[118:121], v[184:187], v[204:207], v[118:121]
	v_mfma_f32_16x16x32_f16 v[86:89], v[180:183], v[216:219], v[86:89]
	v_mfma_f32_16x16x32_f16 v[102:105], v[184:187], v[216:219], v[102:105]
	v_mfma_f32_16x16x32_f16 v[70:73], v[180:183], v[220:223], v[70:73]
	v_mfma_f32_16x16x32_f16 v[78:81], v[184:187], v[220:223], v[78:81]
	v_mfma_f32_16x16x32_f16 v[122:125], v[188:191], v[208:211], v[122:125]
	v_mfma_f32_16x16x32_f16 v[126:129], v[192:195], v[208:211], v[126:129]
	v_mfma_f32_16x16x32_f16 v[110:113], v[188:191], v[212:215], v[110:113]
	v_mfma_f32_16x16x32_f16 v[118:121], v[192:195], v[212:215], v[118:121]
	v_mfma_f32_16x16x32_f16 v[86:89], v[188:191], v[224:227], v[86:89]
	v_mfma_f32_16x16x32_f16 v[102:105], v[192:195], v[224:227], v[102:105]
	v_mfma_f32_16x16x32_f16 v[70:73], v[188:191], v[228:231], v[70:73]
	v_mfma_f32_16x16x32_f16 v[78:81], v[192:195], v[228:231], v[78:81]
	s_barrier
	s_mov_b32 m0, s29
	s_nop 0
	buffer_load_dwordx4 v153, s[8:11], s58 offen lds
	s_mov_b32 m0, s30
	s_add_i32 s55, s55, 0x80080
	buffer_load_dwordx4 v156, s[8:11], s58 offen lds
	s_mov_b32 m0, s35
	s_nop 0
	buffer_load_dwordx4 v153, s[8:11], s55 offen lds
	s_mov_b32 m0, s36
	s_nop 0
	buffer_load_dwordx4 v156, s[8:11], s55 offen lds
	s_mov_b32 m0, s31
	s_nop 0
	buffer_load_dwordx4 v151, s[48:51], s56 offen lds
	s_mov_b32 m0, s34
	s_nop 0
	buffer_load_dwordx4 v155, s[48:51], s56 offen lds
	ds_read_b128 v[196:199], v161 offset:49152
	ds_read_b128 v[204:207], v161 offset:51200
	ds_read_b128 v[208:211], v162 offset:49152
	ds_read_b128 v[212:215], v162 offset:51200
	ds_read_b128 v[216:219], v161 offset:53248
	ds_read_b128 v[220:223], v161 offset:55296
	ds_read_b128 v[224:227], v162 offset:53248
	ds_read_b128 v[228:231], v162 offset:55296
	s_waitcnt vmcnt(8)
	s_waitcnt lgkmcnt(0)
	s_barrier
	s_waitcnt lgkmcnt(0)
	v_mfma_f32_16x16x32_f16 v[54:57], v[164:167], v[196:199], v[54:57]
	v_mfma_f32_16x16x32_f16 v[66:69], v[168:171], v[196:199], v[66:69]
	v_mfma_f32_16x16x32_f16 v[30:33], v[164:167], v[204:207], v[30:33]
	v_mfma_f32_16x16x32_f16 v[38:41], v[168:171], v[204:207], v[38:41]
	v_mfma_f32_16x16x32_f16 v[10:13], v[164:167], v[216:219], v[10:13]
	v_mfma_f32_16x16x32_f16 v[18:21], v[168:171], v[216:219], v[18:21]
	v_mfma_f32_16x16x32_f16 v[2:5], v[164:167], v[220:223], v[2:5]
	v_mfma_f32_16x16x32_f16 v[6:9], v[168:171], v[220:223], v[6:9]
	v_mfma_f32_16x16x32_f16 v[54:57], v[172:175], v[208:211], v[54:57]
	v_mfma_f32_16x16x32_f16 v[66:69], v[176:179], v[208:211], v[66:69]
	v_mfma_f32_16x16x32_f16 v[30:33], v[172:175], v[212:215], v[30:33]
	v_mfma_f32_16x16x32_f16 v[38:41], v[176:179], v[212:215], v[38:41]
	v_mfma_f32_16x16x32_f16 v[10:13], v[172:175], v[224:227], v[10:13]
	v_mfma_f32_16x16x32_f16 v[18:21], v[176:179], v[224:227], v[18:21]
	v_mfma_f32_16x16x32_f16 v[2:5], v[172:175], v[228:231], v[2:5]
	v_mfma_f32_16x16x32_f16 v[6:9], v[176:179], v[228:231], v[6:9]
	v_mfma_f32_16x16x32_f16 v[106:109], v[180:183], v[196:199], v[106:109]
	v_mfma_f32_16x16x32_f16 v[114:117], v[184:187], v[196:199], v[114:117]
	v_mfma_f32_16x16x32_f16 v[82:85], v[180:183], v[204:207], v[82:85]
	v_mfma_f32_16x16x32_f16 v[90:93], v[184:187], v[204:207], v[90:93]
	v_mfma_f32_16x16x32_f16 v[46:49], v[180:183], v[216:219], v[46:49]
	v_mfma_f32_16x16x32_f16 v[58:61], v[184:187], v[216:219], v[58:61]
	v_mfma_f32_16x16x32_f16 v[26:29], v[180:183], v[220:223], v[26:29]
	v_mfma_f32_16x16x32_f16 v[50:53], v[184:187], v[220:223], v[50:53]
	v_mfma_f32_16x16x32_f16 v[106:109], v[188:191], v[208:211], v[106:109]
	v_mfma_f32_16x16x32_f16 v[114:117], v[192:195], v[208:211], v[114:117]
	v_mfma_f32_16x16x32_f16 v[82:85], v[188:191], v[212:215], v[82:85]
	v_mfma_f32_16x16x32_f16 v[90:93], v[192:195], v[212:215], v[90:93]
	v_mfma_f32_16x16x32_f16 v[46:49], v[188:191], v[224:227], v[46:49]
	v_mfma_f32_16x16x32_f16 v[58:61], v[192:195], v[224:227], v[58:61]
	v_mfma_f32_16x16x32_f16 v[26:29], v[188:191], v[228:231], v[26:29]
	v_mfma_f32_16x16x32_f16 v[50:53], v[192:195], v[228:231], v[50:53]
	s_barrier

.Lc0r_first:
	s_add_i32 s81, s64, 0x80
	s_and_b64 s[10:11], s[10:11], exec
	s_cselect_b32 s84, s24, s81
	s_cselect_b32 s85, s25, s65
	s_add_i32 s10, 0, 0x10000
	v_add_u32_e32 v3, s10, v208
	v_add_u32_e32 v144, s10, v209
	s_add_i32 s10, 0, 0x14000
	ds_read_b128 v[116:119], v3
	ds_read_b128 v[120:123], v3 offset:2048
	ds_read_b128 v[140:143], v144
	ds_read_b128 v[144:147], v144 offset:2048
	v_add_u32_e32 v3, s10, v208
	v_add_u32_e32 v176, s10, v209
	s_add_i32 s10, s29, s64
	s_mov_b32 m0, s53
	s_nop 0
	buffer_load_dwordx4 v204, s[48:51], s10 offen lds
	s_mov_b32 m0, s54
	s_nop 0
	buffer_load_dwordx4 v206, s[48:51], s10 offen lds
	ds_read_b128 v[164:167], v3
	ds_read_b128 v[168:171], v3 offset:2048
	ds_read_b128 v[172:175], v176
	ds_read_b128 v[176:179], v176 offset:2048
	s_add_i32 s81, s84, 0x80
	s_add_i32 s82, s85, 0x80
	ds_read_b128 v[180:183], v214
	ds_read_b128 v[184:187], v214 offset:2048
	ds_read_b128 v[188:191], v215
	ds_read_b128 v[192:195], v215 offset:2048
	ds_read_b128 v[196:199], v214 offset:4096
	ds_read_b128 v[216:219], v214 offset:6144
	ds_read_b128 v[220:223], v215 offset:4096
	ds_read_b128 v[224:227], v215 offset:6144
	s_waitcnt vmcnt(8)
	s_waitcnt lgkmcnt(0)
	s_barrier
	s_waitcnt lgkmcnt(0)
	v_mfma_f32_16x16x32_bf16 v[160:163], v[116:119], v[180:183], 0
	v_mfma_f32_16x16x32_bf16 v[152:155], v[120:123], v[180:183], 0
	v_mfma_f32_16x16x32_bf16 v[132:135], v[116:119], v[184:187], 0
	v_mfma_f32_16x16x32_bf16 v[124:127], v[120:123], v[184:187], 0
	v_mfma_f32_16x16x32_bf16 v[108:111], v[116:119], v[196:199], 0
	v_mfma_f32_16x16x32_bf16 v[100:103], v[120:123], v[196:199], 0
	v_mfma_f32_16x16x32_bf16 v[92:95], v[116:119], v[216:219], 0
	v_mfma_f32_16x16x32_bf16 v[84:87], v[120:123], v[216:219], 0
	v_mfma_f32_16x16x32_bf16 v[160:163], v[140:143], v[188:191], v[160:163]
	v_mfma_f32_16x16x32_bf16 v[152:155], v[144:147], v[188:191], v[152:155]
	v_mfma_f32_16x16x32_bf16 v[132:135], v[140:143], v[192:195], v[132:135]
	v_mfma_f32_16x16x32_bf16 v[124:127], v[144:147], v[192:195], v[124:127]
	v_mfma_f32_16x16x32_bf16 v[108:111], v[140:143], v[220:223], v[108:111]
	v_mfma_f32_16x16x32_bf16 v[100:103], v[144:147], v[220:223], v[100:103]
	v_mfma_f32_16x16x32_bf16 v[92:95], v[140:143], v[224:227], v[92:95]
	v_mfma_f32_16x16x32_bf16 v[84:87], v[144:147], v[224:227], v[84:87]
	v_mfma_f32_16x16x32_bf16 v[156:159], v[164:167], v[180:183], 0
	v_mfma_f32_16x16x32_bf16 v[148:151], v[168:171], v[180:183], 0
	v_mfma_f32_16x16x32_bf16 v[136:139], v[164:167], v[184:187], 0
	v_mfma_f32_16x16x32_bf16 v[128:131], v[168:171], v[184:187], 0
	v_mfma_f32_16x16x32_bf16 v[112:115], v[164:167], v[196:199], 0
	v_mfma_f32_16x16x32_bf16 v[104:107], v[168:171], v[196:199], 0
	v_mfma_f32_16x16x32_bf16 v[96:99], v[164:167], v[216:219], 0
	v_mfma_f32_16x16x32_bf16 v[88:91], v[168:171], v[216:219], 0
	v_mfma_f32_16x16x32_bf16 v[156:159], v[172:175], v[188:191], v[156:159]
	v_mfma_f32_16x16x32_bf16 v[148:151], v[176:179], v[188:191], v[148:151]
	v_mfma_f32_16x16x32_bf16 v[136:139], v[172:175], v[192:195], v[136:139]
	v_mfma_f32_16x16x32_bf16 v[128:131], v[176:179], v[192:195], v[128:131]
	v_mfma_f32_16x16x32_bf16 v[112:115], v[172:175], v[220:223], v[112:115]
	v_mfma_f32_16x16x32_bf16 v[104:107], v[176:179], v[220:223], v[104:107]
	v_mfma_f32_16x16x32_bf16 v[96:99], v[172:175], v[224:227], v[96:99]
	v_mfma_f32_16x16x32_bf16 v[88:91], v[176:179], v[224:227], v[88:91]
	s_barrier
	s_mov_b32 s10, s50
	s_mov_b32 s11, s51
	s_mov_b32 m0, s34
	s_nop 0
	buffer_load_dwordx4 v205, s[8:11], s85 offen lds
	s_mov_b32 m0, s35
	s_nop 0
	buffer_load_dwordx4 v207, s[8:11], s85 offen lds
	s_add_i32 s85, s85, s29
	s_mov_b32 m0, s36
	s_nop 0
	buffer_load_dwordx4 v205, s[8:11], s85 offen lds
	s_mov_b32 m0, s37
	s_nop 0
	buffer_load_dwordx4 v207, s[8:11], s85 offen lds
	s_mov_b32 m0, s31
	s_nop 0
	buffer_load_dwordx4 v204, s[48:51], s84 offen lds
	s_mov_b32 m0, s38
	s_nop 0
	buffer_load_dwordx4 v206, s[48:51], s84 offen lds
	ds_read_b128 v[180:183], v214 offset:16384
	ds_read_b128 v[184:187], v214 offset:18432
	ds_read_b128 v[188:191], v215 offset:16384
	ds_read_b128 v[192:195], v215 offset:18432
	ds_read_b128 v[196:199], v214 offset:20480
	ds_read_b128 v[216:219], v214 offset:22528
	ds_read_b128 v[220:223], v215 offset:20480
	ds_read_b128 v[224:227], v215 offset:22528
	s_waitcnt vmcnt(8)
	s_waitcnt lgkmcnt(0)
	s_barrier
	s_waitcnt lgkmcnt(0)
	v_mfma_f32_16x16x32_bf16 v[76:79], v[116:119], v[180:183], 0
	v_mfma_f32_16x16x32_bf16 v[68:71], v[120:123], v[180:183], 0
	v_mfma_f32_16x16x32_bf16 v[60:63], v[116:119], v[184:187], 0
	v_mfma_f32_16x16x32_bf16 v[52:55], v[120:123], v[184:187], 0
	v_mfma_f32_16x16x32_bf16 v[44:47], v[116:119], v[196:199], 0
	v_mfma_f32_16x16x32_bf16 v[36:39], v[120:123], v[196:199], 0
	v_mfma_f32_16x16x32_bf16 v[24:27], v[116:119], v[216:219], 0
	v_mfma_f32_16x16x32_bf16 v[20:23], v[120:123], v[216:219], 0
	v_mfma_f32_16x16x32_bf16 v[76:79], v[140:143], v[188:191], v[76:79]
	v_mfma_f32_16x16x32_bf16 v[68:71], v[144:147], v[188:191], v[68:71]
	v_mfma_f32_16x16x32_bf16 v[60:63], v[140:143], v[192:195], v[60:63]
	v_mfma_f32_16x16x32_bf16 v[52:55], v[144:147], v[192:195], v[52:55]
	v_mfma_f32_16x16x32_bf16 v[44:47], v[140:143], v[220:223], v[44:47]
	v_mfma_f32_16x16x32_bf16 v[36:39], v[144:147], v[220:223], v[36:39]
	v_mfma_f32_16x16x32_bf16 v[24:27], v[140:143], v[224:227], v[24:27]
	v_mfma_f32_16x16x32_bf16 v[20:23], v[144:147], v[224:227], v[20:23]
	v_mfma_f32_16x16x32_bf16 v[80:83], v[164:167], v[180:183], 0
	v_mfma_f32_16x16x32_bf16 v[72:75], v[168:171], v[180:183], 0
	v_mfma_f32_16x16x32_bf16 v[64:67], v[164:167], v[184:187], 0
	v_mfma_f32_16x16x32_bf16 v[56:59], v[168:171], v[184:187], 0
	v_mfma_f32_16x16x32_bf16 v[48:51], v[164:167], v[196:199], 0
	v_mfma_f32_16x16x32_bf16 v[40:43], v[168:171], v[196:199], 0
	v_mfma_f32_16x16x32_bf16 v[28:31], v[164:167], v[216:219], 0
	v_mfma_f32_16x16x32_bf16 v[32:35], v[168:171], v[216:219], 0
	v_mfma_f32_16x16x32_bf16 v[80:83], v[172:175], v[188:191], v[80:83]
	v_mfma_f32_16x16x32_bf16 v[72:75], v[176:179], v[188:191], v[72:75]
	v_mfma_f32_16x16x32_bf16 v[64:67], v[172:175], v[192:195], v[64:67]
	v_mfma_f32_16x16x32_bf16 v[56:59], v[176:179], v[192:195], v[56:59]
	v_mfma_f32_16x16x32_bf16 v[48:51], v[172:175], v[220:223], v[48:51]
	v_mfma_f32_16x16x32_bf16 v[40:43], v[176:179], v[220:223], v[40:43]
	v_mfma_f32_16x16x32_bf16 v[28:31], v[172:175], v[224:227], v[28:31]
	v_mfma_f32_16x16x32_bf16 v[32:35], v[176:179], v[224:227], v[32:35]
	s_barrier
	s_add_i32 s85, 0, 0x18000
	v_add_u32_e32 v3, s85, v208
	v_add_u32_e32 v144, s85, v209
	s_add_i32 s85, 0, 0x1c000
	s_add_i32 s84, s84, s29
	s_mov_b32 m0, s39
	s_nop 0
	buffer_load_dwordx4 v204, s[48:51], s84 offen lds
	s_mov_b32 m0, s40
	s_nop 0
	buffer_load_dwordx4 v206, s[48:51], s84 offen lds
	ds_read_b128 v[116:119], v3
	ds_read_b128 v[120:123], v3 offset:2048
	ds_read_b128 v[140:143], v144
	ds_read_b128 v[144:147], v144 offset:2048
	v_add_u32_e32 v3, s85, v208
	v_add_u32_e32 v176, s85, v209
	ds_read_b128 v[164:167], v3
	ds_read_b128 v[168:171], v3 offset:2048
	ds_read_b128 v[172:175], v176
	ds_read_b128 v[176:179], v176 offset:2048
	ds_read_b128 v[180:183], v214 offset:32768
	ds_read_b128 v[184:187], v214 offset:34816
	ds_read_b128 v[188:191], v215 offset:32768
	ds_read_b128 v[192:195], v215 offset:34816
	ds_read_b128 v[196:199], v214 offset:36864
	ds_read_b128 v[216:219], v214 offset:38912
	ds_read_b128 v[220:223], v215 offset:36864
	ds_read_b128 v[224:227], v215 offset:38912
	s_waitcnt vmcnt(8)
	s_waitcnt lgkmcnt(0)
	s_barrier
	s_waitcnt lgkmcnt(0)
	v_mfma_f32_16x16x32_bf16 v[160:163], v[116:119], v[180:183], v[160:163]
	v_mfma_f32_16x16x32_bf16 v[152:155], v[120:123], v[180:183], v[152:155]
	v_mfma_f32_16x16x32_bf16 v[132:135], v[116:119], v[184:187], v[132:135]
	v_mfma_f32_16x16x32_bf16 v[124:127], v[120:123], v[184:187], v[124:127]
	v_mfma_f32_16x16x32_bf16 v[108:111], v[116:119], v[196:199], v[108:111]
	v_mfma_f32_16x16x32_bf16 v[100:103], v[120:123], v[196:199], v[100:103]
	v_mfma_f32_16x16x32_bf16 v[92:95], v[116:119], v[216:219], v[92:95]
	v_mfma_f32_16x16x32_bf16 v[84:87], v[120:123], v[216:219], v[84:87]
	v_mfma_f32_16x16x32_bf16 v[160:163], v[140:143], v[188:191], v[160:163]
	v_mfma_f32_16x16x32_bf16 v[152:155], v[144:147], v[188:191], v[152:155]
	v_mfma_f32_16x16x32_bf16 v[132:135], v[140:143], v[192:195], v[132:135]
	v_mfma_f32_16x16x32_bf16 v[124:127], v[144:147], v[192:195], v[124:127]
	v_mfma_f32_16x16x32_bf16 v[108:111], v[140:143], v[220:223], v[108:111]
	v_mfma_f32_16x16x32_bf16 v[100:103], v[144:147], v[220:223], v[100:103]
	v_mfma_f32_16x16x32_bf16 v[92:95], v[140:143], v[224:227], v[92:95]
	v_mfma_f32_16x16x32_bf16 v[84:87], v[144:147], v[224:227], v[84:87]
	v_mfma_f32_16x16x32_bf16 v[156:159], v[164:167], v[180:183], v[156:159]
	v_mfma_f32_16x16x32_bf16 v[148:151], v[168:171], v[180:183], v[148:151]
	v_mfma_f32_16x16x32_bf16 v[136:139], v[164:167], v[184:187], v[136:139]
	v_mfma_f32_16x16x32_bf16 v[128:131], v[168:171], v[184:187], v[128:131]
	v_mfma_f32_16x16x32_bf16 v[112:115], v[164:167], v[196:199], v[112:115]
	v_mfma_f32_16x16x32_bf16 v[104:107], v[168:171], v[196:199], v[104:107]
	v_mfma_f32_16x16x32_bf16 v[96:99], v[164:167], v[216:219], v[96:99]
	v_mfma_f32_16x16x32_bf16 v[88:91], v[168:171], v[216:219], v[88:91]
	v_mfma_f32_16x16x32_bf16 v[156:159], v[172:175], v[188:191], v[156:159]
	v_mfma_f32_16x16x32_bf16 v[148:151], v[176:179], v[188:191], v[148:151]
	v_mfma_f32_16x16x32_bf16 v[136:139], v[172:175], v[192:195], v[136:139]
	v_mfma_f32_16x16x32_bf16 v[128:131], v[176:179], v[192:195], v[128:131]
	v_mfma_f32_16x16x32_bf16 v[112:115], v[172:175], v[220:223], v[112:115]
	v_mfma_f32_16x16x32_bf16 v[104:107], v[176:179], v[220:223], v[104:107]
	v_mfma_f32_16x16x32_bf16 v[96:99], v[172:175], v[224:227], v[96:99]
	v_mfma_f32_16x16x32_bf16 v[88:91], v[176:179], v[224:227], v[88:91]
	s_barrier
	s_mov_b32 m0, s41
	s_nop 0
	buffer_load_dwordx4 v205, s[8:11], s82 offen lds
	s_mov_b32 m0, s42
	s_nop 0
	buffer_load_dwordx4 v207, s[8:11], s82 offen lds
	s_add_i32 s82, s82, s29
	s_mov_b32 m0, s45
	s_nop 0
	buffer_load_dwordx4 v205, s[8:11], s82 offen lds
	s_mov_b32 m0, s46
	s_nop 0
	buffer_load_dwordx4 v207, s[8:11], s82 offen lds
	s_mov_b32 m0, s43
	s_nop 0
	buffer_load_dwordx4 v204, s[48:51], s81 offen lds
	s_mov_b32 m0, s44
	s_nop 0
	buffer_load_dwordx4 v206, s[48:51], s81 offen lds
	ds_read_b128 v[180:183], v214 offset:49152
	ds_read_b128 v[184:187], v214 offset:51200
	ds_read_b128 v[188:191], v215 offset:49152
	ds_read_b128 v[192:195], v215 offset:51200
	ds_read_b128 v[196:199], v214 offset:53248
	ds_read_b128 v[216:219], v214 offset:55296
	ds_read_b128 v[220:223], v215 offset:53248
	ds_read_b128 v[224:227], v215 offset:55296
	s_waitcnt vmcnt(8)
	s_waitcnt lgkmcnt(0)
	s_barrier
	s_waitcnt lgkmcnt(0)
	v_mfma_f32_16x16x32_bf16 v[76:79], v[116:119], v[180:183], v[76:79]
	v_mfma_f32_16x16x32_bf16 v[68:71], v[120:123], v[180:183], v[68:71]
	v_mfma_f32_16x16x32_bf16 v[60:63], v[116:119], v[184:187], v[60:63]
	v_mfma_f32_16x16x32_bf16 v[52:55], v[120:123], v[184:187], v[52:55]
	v_mfma_f32_16x16x32_bf16 v[44:47], v[116:119], v[196:199], v[44:47]
	v_mfma_f32_16x16x32_bf16 v[36:39], v[120:123], v[196:199], v[36:39]
	v_mfma_f32_16x16x32_bf16 v[24:27], v[116:119], v[216:219], v[24:27]
	v_mfma_f32_16x16x32_bf16 v[20:23], v[120:123], v[216:219], v[20:23]
	v_mfma_f32_16x16x32_bf16 v[76:79], v[140:143], v[188:191], v[76:79]
	v_mfma_f32_16x16x32_bf16 v[68:71], v[144:147], v[188:191], v[68:71]
	v_mfma_f32_16x16x32_bf16 v[60:63], v[140:143], v[192:195], v[60:63]
	v_mfma_f32_16x16x32_bf16 v[52:55], v[144:147], v[192:195], v[52:55]
	v_mfma_f32_16x16x32_bf16 v[44:47], v[140:143], v[220:223], v[44:47]
	v_mfma_f32_16x16x32_bf16 v[36:39], v[144:147], v[220:223], v[36:39]
	v_mfma_f32_16x16x32_bf16 v[24:27], v[140:143], v[224:227], v[24:27]
	v_mfma_f32_16x16x32_bf16 v[20:23], v[144:147], v[224:227], v[20:23]
	v_mfma_f32_16x16x32_bf16 v[80:83], v[164:167], v[180:183], v[80:83]
	v_mfma_f32_16x16x32_bf16 v[72:75], v[168:171], v[180:183], v[72:75]
	v_mfma_f32_16x16x32_bf16 v[64:67], v[164:167], v[184:187], v[64:67]
	v_mfma_f32_16x16x32_bf16 v[56:59], v[168:171], v[184:187], v[56:59]
	v_mfma_f32_16x16x32_bf16 v[48:51], v[164:167], v[196:199], v[48:51]
	v_mfma_f32_16x16x32_bf16 v[40:43], v[168:171], v[196:199], v[40:43]
	v_mfma_f32_16x16x32_bf16 v[28:31], v[164:167], v[216:219], v[28:31]
	v_mfma_f32_16x16x32_bf16 v[32:35], v[168:171], v[216:219], v[32:35]
	v_mfma_f32_16x16x32_bf16 v[80:83], v[172:175], v[188:191], v[80:83]
	v_mfma_f32_16x16x32_bf16 v[72:75], v[176:179], v[188:191], v[72:75]
	v_mfma_f32_16x16x32_bf16 v[64:67], v[172:175], v[192:195], v[64:67]
	v_mfma_f32_16x16x32_bf16 v[56:59], v[176:179], v[192:195], v[56:59]
	v_mfma_f32_16x16x32_bf16 v[48:51], v[172:175], v[220:223], v[48:51]
	v_mfma_f32_16x16x32_bf16 v[40:43], v[176:179], v[220:223], v[40:43]
	v_mfma_f32_16x16x32_bf16 v[28:31], v[172:175], v[224:227], v[28:31]
	v_mfma_f32_16x16x32_bf16 v[32:35], v[176:179], v[224:227], v[32:35]
	s_barrier
	s_branch .Lc0r_tail
.Lc0r_final:
	s_add_i32 s81, s64, 0x80
	s_and_b64 s[10:11], s[10:11], exec
	s_cselect_b32 s84, s24, s81
	s_cselect_b32 s85, s25, s65
	s_add_i32 s10, 0, 0x10000
	v_add_u32_e32 v3, s10, v208
	v_add_u32_e32 v144, s10, v209
	s_add_i32 s10, 0, 0x14000
	ds_read_b128 v[116:119], v3
	ds_read_b128 v[120:123], v3 offset:2048
	ds_read_b128 v[140:143], v144
	ds_read_b128 v[144:147], v144 offset:2048
	v_add_u32_e32 v3, s10, v208
	v_add_u32_e32 v176, s10, v209
	s_add_i32 s10, s29, s64
	s_mov_b32 m0, s53
	s_nop 0
	buffer_load_dwordx4 v204, s[48:51], s10 offen lds
	s_mov_b32 m0, s54
	s_nop 0
	buffer_load_dwordx4 v206, s[48:51], s10 offen lds
	ds_read_b128 v[164:167], v3
	ds_read_b128 v[168:171], v3 offset:2048
	ds_read_b128 v[172:175], v176
	ds_read_b128 v[176:179], v176 offset:2048
	s_add_i32 s81, s84, 0x80
	s_add_i32 s82, s85, 0x80
	ds_read_b128 v[180:183], v214
	ds_read_b128 v[184:187], v214 offset:2048
	ds_read_b128 v[188:191], v215
	ds_read_b128 v[192:195], v215 offset:2048
	ds_read_b128 v[196:199], v214 offset:4096
	ds_read_b128 v[216:219], v214 offset:6144
	ds_read_b128 v[220:223], v215 offset:4096
	ds_read_b128 v[224:227], v215 offset:6144
	s_waitcnt vmcnt(8)
	s_waitcnt lgkmcnt(0)
	s_barrier
	s_waitcnt lgkmcnt(0)
	v_mfma_f32_16x16x32_bf16 v[160:163], v[116:119], v[180:183], v[160:163]
	v_mfma_f32_16x16x32_bf16 v[152:155], v[120:123], v[180:183], v[152:155]
	v_mfma_f32_16x16x32_bf16 v[132:135], v[116:119], v[184:187], v[132:135]
	v_mfma_f32_16x16x32_bf16 v[124:127], v[120:123], v[184:187], v[124:127]
	v_mfma_f32_16x16x32_bf16 v[108:111], v[116:119], v[196:199], v[108:111]
	v_mfma_f32_16x16x32_bf16 v[100:103], v[120:123], v[196:199], v[100:103]
	v_mfma_f32_16x16x32_bf16 v[92:95], v[116:119], v[216:219], v[92:95]
	v_mfma_f32_16x16x32_bf16 v[84:87], v[120:123], v[216:219], v[84:87]
	v_mfma_f32_16x16x32_bf16 v[160:163], v[140:143], v[188:191], v[160:163]
	v_mfma_f32_16x16x32_bf16 v[152:155], v[144:147], v[188:191], v[152:155]
	v_mfma_f32_16x16x32_bf16 v[132:135], v[140:143], v[192:195], v[132:135]
	v_mfma_f32_16x16x32_bf16 v[124:127], v[144:147], v[192:195], v[124:127]
	v_mfma_f32_16x16x32_bf16 v[108:111], v[140:143], v[220:223], v[108:111]
	v_mfma_f32_16x16x32_bf16 v[100:103], v[144:147], v[220:223], v[100:103]
	v_mfma_f32_16x16x32_bf16 v[92:95], v[140:143], v[224:227], v[92:95]
	v_mfma_f32_16x16x32_bf16 v[84:87], v[144:147], v[224:227], v[84:87]
	v_mfma_f32_16x16x32_bf16 v[156:159], v[164:167], v[180:183], v[156:159]
	v_mfma_f32_16x16x32_bf16 v[148:151], v[168:171], v[180:183], v[148:151]
	v_mfma_f32_16x16x32_bf16 v[136:139], v[164:167], v[184:187], v[136:139]
	v_mfma_f32_16x16x32_bf16 v[128:131], v[168:171], v[184:187], v[128:131]
	v_mfma_f32_16x16x32_bf16 v[112:115], v[164:167], v[196:199], v[112:115]
	v_mfma_f32_16x16x32_bf16 v[104:107], v[168:171], v[196:199], v[104:107]
	v_mfma_f32_16x16x32_bf16 v[96:99], v[164:167], v[216:219], v[96:99]
	v_mfma_f32_16x16x32_bf16 v[88:91], v[168:171], v[216:219], v[88:91]
	v_mfma_f32_16x16x32_bf16 v[156:159], v[172:175], v[188:191], v[156:159]
	v_mfma_f32_16x16x32_bf16 v[148:151], v[176:179], v[188:191], v[148:151]
	v_mfma_f32_16x16x32_bf16 v[136:139], v[172:175], v[192:195], v[136:139]
	v_mfma_f32_16x16x32_bf16 v[128:131], v[176:179], v[192:195], v[128:131]
	v_mfma_f32_16x16x32_bf16 v[112:115], v[172:175], v[220:223], v[112:115]
	v_mfma_f32_16x16x32_bf16 v[104:107], v[176:179], v[220:223], v[104:107]
	v_mfma_f32_16x16x32_bf16 v[96:99], v[172:175], v[224:227], v[96:99]
	v_mfma_f32_16x16x32_bf16 v[88:91], v[176:179], v[224:227], v[88:91]
	s_barrier
	s_mov_b32 s10, s50
	s_mov_b32 s11, s51
	ds_read_b128 v[180:183], v214 offset:16384
	ds_read_b128 v[184:187], v214 offset:18432
	ds_read_b128 v[188:191], v215 offset:16384
	ds_read_b128 v[192:195], v215 offset:18432
	ds_read_b128 v[196:199], v214 offset:20480
	ds_read_b128 v[216:219], v214 offset:22528
	ds_read_b128 v[220:223], v215 offset:20480
	ds_read_b128 v[224:227], v215 offset:22528
	s_add_i32 s85, s85, s29
	s_waitcnt vmcnt(2)
	s_waitcnt lgkmcnt(0)
	s_barrier
	s_waitcnt lgkmcnt(0)
	v_mfma_f32_16x16x32_bf16 v[76:79], v[116:119], v[180:183], v[76:79]
	v_mfma_f32_16x16x32_bf16 v[68:71], v[120:123], v[180:183], v[68:71]
	v_mfma_f32_16x16x32_bf16 v[60:63], v[116:119], v[184:187], v[60:63]
	v_mfma_f32_16x16x32_bf16 v[52:55], v[120:123], v[184:187], v[52:55]
	v_mfma_f32_16x16x32_bf16 v[44:47], v[116:119], v[196:199], v[44:47]
	v_mfma_f32_16x16x32_bf16 v[36:39], v[120:123], v[196:199], v[36:39]
	v_mfma_f32_16x16x32_bf16 v[24:27], v[116:119], v[216:219], v[24:27]
	v_mfma_f32_16x16x32_bf16 v[20:23], v[120:123], v[216:219], v[20:23]
	v_mfma_f32_16x16x32_bf16 v[76:79], v[140:143], v[188:191], v[76:79]
	v_mfma_f32_16x16x32_bf16 v[68:71], v[144:147], v[188:191], v[68:71]
	v_mfma_f32_16x16x32_bf16 v[60:63], v[140:143], v[192:195], v[60:63]
	v_mfma_f32_16x16x32_bf16 v[52:55], v[144:147], v[192:195], v[52:55]
	v_mfma_f32_16x16x32_bf16 v[44:47], v[140:143], v[220:223], v[44:47]
	v_mfma_f32_16x16x32_bf16 v[36:39], v[144:147], v[220:223], v[36:39]
	v_mfma_f32_16x16x32_bf16 v[24:27], v[140:143], v[224:227], v[24:27]
	v_mfma_f32_16x16x32_bf16 v[20:23], v[144:147], v[224:227], v[20:23]
	v_mfma_f32_16x16x32_bf16 v[80:83], v[164:167], v[180:183], v[80:83]
	v_mfma_f32_16x16x32_bf16 v[72:75], v[168:171], v[180:183], v[72:75]
	v_mfma_f32_16x16x32_bf16 v[64:67], v[164:167], v[184:187], v[64:67]
	v_mfma_f32_16x16x32_bf16 v[56:59], v[168:171], v[184:187], v[56:59]
	v_mfma_f32_16x16x32_bf16 v[48:51], v[164:167], v[196:199], v[48:51]
	v_mfma_f32_16x16x32_bf16 v[40:43], v[168:171], v[196:199], v[40:43]
	v_mfma_f32_16x16x32_bf16 v[28:31], v[164:167], v[216:219], v[28:31]
	v_mfma_f32_16x16x32_bf16 v[32:35], v[168:171], v[216:219], v[32:35]
	v_mfma_f32_16x16x32_bf16 v[80:83], v[172:175], v[188:191], v[80:83]
	v_mfma_f32_16x16x32_bf16 v[72:75], v[176:179], v[188:191], v[72:75]
	v_mfma_f32_16x16x32_bf16 v[64:67], v[172:175], v[192:195], v[64:67]
	v_mfma_f32_16x16x32_bf16 v[56:59], v[176:179], v[192:195], v[56:59]
	v_mfma_f32_16x16x32_bf16 v[48:51], v[172:175], v[220:223], v[48:51]
	v_mfma_f32_16x16x32_bf16 v[40:43], v[176:179], v[220:223], v[40:43]
	v_mfma_f32_16x16x32_bf16 v[28:31], v[172:175], v[224:227], v[28:31]
	v_mfma_f32_16x16x32_bf16 v[32:35], v[176:179], v[224:227], v[32:35]
	s_barrier
	s_add_i32 s85, 0, 0x18000
	v_add_u32_e32 v3, s85, v208
	v_add_u32_e32 v144, s85, v209
	s_add_i32 s85, 0, 0x1c000
	ds_read_b128 v[116:119], v3
	ds_read_b128 v[120:123], v3 offset:2048
	ds_read_b128 v[140:143], v144
	ds_read_b128 v[144:147], v144 offset:2048
	v_add_u32_e32 v3, s85, v208
	v_add_u32_e32 v176, s85, v209
	ds_read_b128 v[164:167], v3
	ds_read_b128 v[168:171], v3 offset:2048
	ds_read_b128 v[172:175], v176
	ds_read_b128 v[176:179], v176 offset:2048
	s_add_i32 s84, s84, s29
	ds_read_b128 v[180:183], v214 offset:32768
	ds_read_b128 v[184:187], v214 offset:34816
	ds_read_b128 v[188:191], v215 offset:32768
	ds_read_b128 v[192:195], v215 offset:34816
	ds_read_b128 v[196:199], v214 offset:36864
	ds_read_b128 v[216:219], v214 offset:38912
	ds_read_b128 v[220:223], v215 offset:36864
	ds_read_b128 v[224:227], v215 offset:38912
	s_waitcnt vmcnt(0)
	s_waitcnt lgkmcnt(0)
	s_barrier
	s_waitcnt lgkmcnt(0)
	v_mfma_f32_16x16x32_bf16 v[160:163], v[116:119], v[180:183], v[160:163]
	v_mfma_f32_16x16x32_bf16 v[152:155], v[120:123], v[180:183], v[152:155]
	v_mfma_f32_16x16x32_bf16 v[132:135], v[116:119], v[184:187], v[132:135]
	v_mfma_f32_16x16x32_bf16 v[124:127], v[120:123], v[184:187], v[124:127]
	v_mfma_f32_16x16x32_bf16 v[108:111], v[116:119], v[196:199], v[108:111]
	v_mfma_f32_16x16x32_bf16 v[100:103], v[120:123], v[196:199], v[100:103]
	v_mfma_f32_16x16x32_bf16 v[92:95], v[116:119], v[216:219], v[92:95]
	v_mfma_f32_16x16x32_bf16 v[84:87], v[120:123], v[216:219], v[84:87]
	v_mfma_f32_16x16x32_bf16 v[160:163], v[140:143], v[188:191], v[160:163]
	v_mfma_f32_16x16x32_bf16 v[152:155], v[144:147], v[188:191], v[152:155]
	v_mfma_f32_16x16x32_bf16 v[132:135], v[140:143], v[192:195], v[132:135]
	v_mfma_f32_16x16x32_bf16 v[124:127], v[144:147], v[192:195], v[124:127]
	v_mfma_f32_16x16x32_bf16 v[108:111], v[140:143], v[220:223], v[108:111]
	v_mfma_f32_16x16x32_bf16 v[100:103], v[144:147], v[220:223], v[100:103]
	v_mfma_f32_16x16x32_bf16 v[92:95], v[140:143], v[224:227], v[92:95]
	v_mfma_f32_16x16x32_bf16 v[84:87], v[144:147], v[224:227], v[84:87]
	v_mfma_f32_16x16x32_bf16 v[156:159], v[164:167], v[180:183], v[156:159]
	v_mfma_f32_16x16x32_bf16 v[148:151], v[168:171], v[180:183], v[148:151]
	v_mfma_f32_16x16x32_bf16 v[136:139], v[164:167], v[184:187], v[136:139]
	v_mfma_f32_16x16x32_bf16 v[128:131], v[168:171], v[184:187], v[128:131]
	v_mfma_f32_16x16x32_bf16 v[112:115], v[164:167], v[196:199], v[112:115]
	v_mfma_f32_16x16x32_bf16 v[104:107], v[168:171], v[196:199], v[104:107]
	v_mfma_f32_16x16x32_bf16 v[96:99], v[164:167], v[216:219], v[96:99]
	v_mfma_f32_16x16x32_bf16 v[88:91], v[168:171], v[216:219], v[88:91]
	v_mfma_f32_16x16x32_bf16 v[156:159], v[172:175], v[188:191], v[156:159]
	v_mfma_f32_16x16x32_bf16 v[148:151], v[176:179], v[188:191], v[148:151]
	v_mfma_f32_16x16x32_bf16 v[136:139], v[172:175], v[192:195], v[136:139]
	v_mfma_f32_16x16x32_bf16 v[128:131], v[176:179], v[192:195], v[128:131]
	v_mfma_f32_16x16x32_bf16 v[112:115], v[172:175], v[220:223], v[112:115]
	v_mfma_f32_16x16x32_bf16 v[104:107], v[176:179], v[220:223], v[104:107]
	v_mfma_f32_16x16x32_bf16 v[96:99], v[172:175], v[224:227], v[96:99]
	v_mfma_f32_16x16x32_bf16 v[88:91], v[176:179], v[224:227], v[88:91]
	s_barrier
	ds_read_b128 v[180:183], v214 offset:49152
	ds_read_b128 v[184:187], v214 offset:51200
	ds_read_b128 v[188:191], v215 offset:49152
	ds_read_b128 v[192:195], v215 offset:51200
	ds_read_b128 v[196:199], v214 offset:53248
	ds_read_b128 v[216:219], v214 offset:55296
	ds_read_b128 v[220:223], v215 offset:53248
	ds_read_b128 v[224:227], v215 offset:55296
	s_add_i32 s82, s82, s29
	s_waitcnt vmcnt(0)
	s_waitcnt lgkmcnt(0)
	s_barrier
	s_waitcnt lgkmcnt(0)
	v_mfma_f32_16x16x32_bf16 v[76:79], v[116:119], v[180:183], v[76:79]
	v_mfma_f32_16x16x32_bf16 v[68:71], v[120:123], v[180:183], v[68:71]
	v_mfma_f32_16x16x32_bf16 v[60:63], v[116:119], v[184:187], v[60:63]
	v_mfma_f32_16x16x32_bf16 v[52:55], v[120:123], v[184:187], v[52:55]
	v_mfma_f32_16x16x32_bf16 v[44:47], v[116:119], v[196:199], v[44:47]
	v_mfma_f32_16x16x32_bf16 v[36:39], v[120:123], v[196:199], v[36:39]
	v_mfma_f32_16x16x32_bf16 v[24:27], v[116:119], v[216:219], v[24:27]
	v_mfma_f32_16x16x32_bf16 v[20:23], v[120:123], v[216:219], v[20:23]
	v_mfma_f32_16x16x32_bf16 v[76:79], v[140:143], v[188:191], v[76:79]
	v_mfma_f32_16x16x32_bf16 v[68:71], v[144:147], v[188:191], v[68:71]
	v_mfma_f32_16x16x32_bf16 v[60:63], v[140:143], v[192:195], v[60:63]
	v_mfma_f32_16x16x32_bf16 v[52:55], v[144:147], v[192:195], v[52:55]
	v_mfma_f32_16x16x32_bf16 v[44:47], v[140:143], v[220:223], v[44:47]
	v_mfma_f32_16x16x32_bf16 v[36:39], v[144:147], v[220:223], v[36:39]
	v_mfma_f32_16x16x32_bf16 v[24:27], v[140:143], v[224:227], v[24:27]
	v_mfma_f32_16x16x32_bf16 v[20:23], v[144:147], v[224:227], v[20:23]
	v_mfma_f32_16x16x32_bf16 v[80:83], v[164:167], v[180:183], v[80:83]
	v_mfma_f32_16x16x32_bf16 v[72:75], v[168:171], v[180:183], v[72:75]
	v_mfma_f32_16x16x32_bf16 v[64:67], v[164:167], v[184:187], v[64:67]
	v_mfma_f32_16x16x32_bf16 v[56:59], v[168:171], v[184:187], v[56:59]
	v_mfma_f32_16x16x32_bf16 v[48:51], v[164:167], v[196:199], v[48:51]
	v_mfma_f32_16x16x32_bf16 v[40:43], v[168:171], v[196:199], v[40:43]
	v_mfma_f32_16x16x32_bf16 v[28:31], v[164:167], v[216:219], v[28:31]
	v_mfma_f32_16x16x32_bf16 v[32:35], v[168:171], v[216:219], v[32:35]
	v_mfma_f32_16x16x32_bf16 v[80:83], v[172:175], v[188:191], v[80:83]
	v_mfma_f32_16x16x32_bf16 v[72:75], v[176:179], v[188:191], v[72:75]
	v_mfma_f32_16x16x32_bf16 v[64:67], v[172:175], v[192:195], v[64:67]
	v_mfma_f32_16x16x32_bf16 v[56:59], v[176:179], v[192:195], v[56:59]
	v_mfma_f32_16x16x32_bf16 v[48:51], v[172:175], v[220:223], v[48:51]
	v_mfma_f32_16x16x32_bf16 v[40:43], v[176:179], v[220:223], v[40:43]
	v_mfma_f32_16x16x32_bf16 v[28:31], v[172:175], v[224:227], v[28:31]
	v_mfma_f32_16x16x32_bf16 v[32:35], v[176:179], v[224:227], v[32:35]
	s_barrier
	s_branch .Lc0r_tail

.Lc0r_norm:
	s_add_i32 s81, s64, 0x80
	s_and_b64 s[10:11], s[10:11], exec
	s_cselect_b32 s84, s24, s81
	s_cselect_b32 s85, s25, s65
	s_add_i32 s10, 0, 0x10000
	v_add_u32_e32 v3, s10, v208
	v_add_u32_e32 v144, s10, v209
	s_add_i32 s10, 0, 0x14000
	ds_read_b128 v[116:119], v3
	ds_read_b128 v[120:123], v3 offset:2048
	ds_read_b128 v[140:143], v144
	ds_read_b128 v[144:147], v144 offset:2048
	v_add_u32_e32 v3, s10, v208
	v_add_u32_e32 v176, s10, v209
	s_add_i32 s10, s29, s64
	s_mov_b32 m0, s53
	s_nop 0
	buffer_load_dwordx4 v204, s[48:51], s10 offen lds
	s_mov_b32 m0, s54
	s_nop 0
	buffer_load_dwordx4 v206, s[48:51], s10 offen lds
	ds_read_b128 v[164:167], v3
	ds_read_b128 v[168:171], v3 offset:2048
	ds_read_b128 v[172:175], v176
	ds_read_b128 v[176:179], v176 offset:2048
	s_add_i32 s81, s84, 0x80
	s_add_i32 s82, s85, 0x80
	ds_read_b128 v[180:183], v214
	ds_read_b128 v[184:187], v214 offset:2048
	ds_read_b128 v[188:191], v215
	ds_read_b128 v[192:195], v215 offset:2048
	ds_read_b128 v[196:199], v214 offset:4096
	ds_read_b128 v[216:219], v214 offset:6144
	ds_read_b128 v[220:223], v215 offset:4096
	ds_read_b128 v[224:227], v215 offset:6144
	s_waitcnt vmcnt(8)
	s_waitcnt lgkmcnt(0)
	s_barrier
	s_waitcnt lgkmcnt(0)
	v_mfma_f32_16x16x32_bf16 v[160:163], v[116:119], v[180:183], v[160:163]
	v_mfma_f32_16x16x32_bf16 v[152:155], v[120:123], v[180:183], v[152:155]
	v_mfma_f32_16x16x32_bf16 v[132:135], v[116:119], v[184:187], v[132:135]
	v_mfma_f32_16x16x32_bf16 v[124:127], v[120:123], v[184:187], v[124:127]
	v_mfma_f32_16x16x32_bf16 v[108:111], v[116:119], v[196:199], v[108:111]
	v_mfma_f32_16x16x32_bf16 v[100:103], v[120:123], v[196:199], v[100:103]
	v_mfma_f32_16x16x32_bf16 v[92:95], v[116:119], v[216:219], v[92:95]
	v_mfma_f32_16x16x32_bf16 v[84:87], v[120:123], v[216:219], v[84:87]
	v_mfma_f32_16x16x32_bf16 v[160:163], v[140:143], v[188:191], v[160:163]
	v_mfma_f32_16x16x32_bf16 v[152:155], v[144:147], v[188:191], v[152:155]
	v_mfma_f32_16x16x32_bf16 v[132:135], v[140:143], v[192:195], v[132:135]
	v_mfma_f32_16x16x32_bf16 v[124:127], v[144:147], v[192:195], v[124:127]
	v_mfma_f32_16x16x32_bf16 v[108:111], v[140:143], v[220:223], v[108:111]
	v_mfma_f32_16x16x32_bf16 v[100:103], v[144:147], v[220:223], v[100:103]
	v_mfma_f32_16x16x32_bf16 v[92:95], v[140:143], v[224:227], v[92:95]
	v_mfma_f32_16x16x32_bf16 v[84:87], v[144:147], v[224:227], v[84:87]
	v_mfma_f32_16x16x32_bf16 v[156:159], v[164:167], v[180:183], v[156:159]
	v_mfma_f32_16x16x32_bf16 v[148:151], v[168:171], v[180:183], v[148:151]
	v_mfma_f32_16x16x32_bf16 v[136:139], v[164:167], v[184:187], v[136:139]
	v_mfma_f32_16x16x32_bf16 v[128:131], v[168:171], v[184:187], v[128:131]
	v_mfma_f32_16x16x32_bf16 v[112:115], v[164:167], v[196:199], v[112:115]
	v_mfma_f32_16x16x32_bf16 v[104:107], v[168:171], v[196:199], v[104:107]
	v_mfma_f32_16x16x32_bf16 v[96:99], v[164:167], v[216:219], v[96:99]
	v_mfma_f32_16x16x32_bf16 v[88:91], v[168:171], v[216:219], v[88:91]
	v_mfma_f32_16x16x32_bf16 v[156:159], v[172:175], v[188:191], v[156:159]
	v_mfma_f32_16x16x32_bf16 v[148:151], v[176:179], v[188:191], v[148:151]
	v_mfma_f32_16x16x32_bf16 v[136:139], v[172:175], v[192:195], v[136:139]
	v_mfma_f32_16x16x32_bf16 v[128:131], v[176:179], v[192:195], v[128:131]
	v_mfma_f32_16x16x32_bf16 v[112:115], v[172:175], v[220:223], v[112:115]
	v_mfma_f32_16x16x32_bf16 v[104:107], v[176:179], v[220:223], v[104:107]
	v_mfma_f32_16x16x32_bf16 v[96:99], v[172:175], v[224:227], v[96:99]
	v_mfma_f32_16x16x32_bf16 v[88:91], v[176:179], v[224:227], v[88:91]
	s_barrier
	s_mov_b32 s10, s50
	s_mov_b32 s11, s51
	s_mov_b32 m0, s34
	s_nop 0
	buffer_load_dwordx4 v205, s[8:11], s85 offen lds
	s_mov_b32 m0, s35
	s_nop 0
	buffer_load_dwordx4 v207, s[8:11], s85 offen lds
	s_add_i32 s85, s85, s29
	s_mov_b32 m0, s36
	s_nop 0
	buffer_load_dwordx4 v205, s[8:11], s85 offen lds
	s_mov_b32 m0, s37
	s_nop 0
	buffer_load_dwordx4 v207, s[8:11], s85 offen lds
	s_mov_b32 m0, s31
	s_nop 0
	buffer_load_dwordx4 v204, s[48:51], s84 offen lds
	s_mov_b32 m0, s38
	s_nop 0
	buffer_load_dwordx4 v206, s[48:51], s84 offen lds
	ds_read_b128 v[180:183], v214 offset:16384
	ds_read_b128 v[184:187], v214 offset:18432
	ds_read_b128 v[188:191], v215 offset:16384
	ds_read_b128 v[192:195], v215 offset:18432
	ds_read_b128 v[196:199], v214 offset:20480
	ds_read_b128 v[216:219], v214 offset:22528
	ds_read_b128 v[220:223], v215 offset:20480
	ds_read_b128 v[224:227], v215 offset:22528
	s_waitcnt vmcnt(8)
	s_waitcnt lgkmcnt(0)
	s_barrier
	s_waitcnt lgkmcnt(0)
	v_mfma_f32_16x16x32_bf16 v[76:79], v[116:119], v[180:183], v[76:79]
	v_mfma_f32_16x16x32_bf16 v[68:71], v[120:123], v[180:183], v[68:71]
	v_mfma_f32_16x16x32_bf16 v[60:63], v[116:119], v[184:187], v[60:63]
	v_mfma_f32_16x16x32_bf16 v[52:55], v[120:123], v[184:187], v[52:55]
	v_mfma_f32_16x16x32_bf16 v[44:47], v[116:119], v[196:199], v[44:47]
	v_mfma_f32_16x16x32_bf16 v[36:39], v[120:123], v[196:199], v[36:39]
	v_mfma_f32_16x16x32_bf16 v[24:27], v[116:119], v[216:219], v[24:27]
	v_mfma_f32_16x16x32_bf16 v[20:23], v[120:123], v[216:219], v[20:23]
	v_mfma_f32_16x16x32_bf16 v[76:79], v[140:143], v[188:191], v[76:79]
	v_mfma_f32_16x16x32_bf16 v[68:71], v[144:147], v[188:191], v[68:71]
	v_mfma_f32_16x16x32_bf16 v[60:63], v[140:143], v[192:195], v[60:63]
	v_mfma_f32_16x16x32_bf16 v[52:55], v[144:147], v[192:195], v[52:55]
	v_mfma_f32_16x16x32_bf16 v[44:47], v[140:143], v[220:223], v[44:47]
	v_mfma_f32_16x16x32_bf16 v[36:39], v[144:147], v[220:223], v[36:39]
	v_mfma_f32_16x16x32_bf16 v[24:27], v[140:143], v[224:227], v[24:27]
	v_mfma_f32_16x16x32_bf16 v[20:23], v[144:147], v[224:227], v[20:23]
	v_mfma_f32_16x16x32_bf16 v[80:83], v[164:167], v[180:183], v[80:83]
	v_mfma_f32_16x16x32_bf16 v[72:75], v[168:171], v[180:183], v[72:75]
	v_mfma_f32_16x16x32_bf16 v[64:67], v[164:167], v[184:187], v[64:67]
	v_mfma_f32_16x16x32_bf16 v[56:59], v[168:171], v[184:187], v[56:59]
	v_mfma_f32_16x16x32_bf16 v[48:51], v[164:167], v[196:199], v[48:51]
	v_mfma_f32_16x16x32_bf16 v[40:43], v[168:171], v[196:199], v[40:43]
	v_mfma_f32_16x16x32_bf16 v[28:31], v[164:167], v[216:219], v[28:31]
	v_mfma_f32_16x16x32_bf16 v[32:35], v[168:171], v[216:219], v[32:35]
	v_mfma_f32_16x16x32_bf16 v[80:83], v[172:175], v[188:191], v[80:83]
	v_mfma_f32_16x16x32_bf16 v[72:75], v[176:179], v[188:191], v[72:75]
	v_mfma_f32_16x16x32_bf16 v[64:67], v[172:175], v[192:195], v[64:67]
	v_mfma_f32_16x16x32_bf16 v[56:59], v[176:179], v[192:195], v[56:59]
	v_mfma_f32_16x16x32_bf16 v[48:51], v[172:175], v[220:223], v[48:51]
	v_mfma_f32_16x16x32_bf16 v[40:43], v[176:179], v[220:223], v[40:43]
	v_mfma_f32_16x16x32_bf16 v[28:31], v[172:175], v[224:227], v[28:31]
	v_mfma_f32_16x16x32_bf16 v[32:35], v[176:179], v[224:227], v[32:35]
	s_barrier
	s_add_i32 s85, 0, 0x18000
	v_add_u32_e32 v3, s85, v208
	v_add_u32_e32 v144, s85, v209
	s_add_i32 s85, 0, 0x1c000
	s_add_i32 s84, s84, s29
	s_mov_b32 m0, s39
	s_nop 0
	buffer_load_dwordx4 v204, s[48:51], s84 offen lds
	s_mov_b32 m0, s40
	s_nop 0
	buffer_load_dwordx4 v206, s[48:51], s84 offen lds
	ds_read_b128 v[116:119], v3
	ds_read_b128 v[120:123], v3 offset:2048
	ds_read_b128 v[140:143], v144
	ds_read_b128 v[144:147], v144 offset:2048
	v_add_u32_e32 v3, s85, v208
	v_add_u32_e32 v176, s85, v209
	ds_read_b128 v[164:167], v3
	ds_read_b128 v[168:171], v3 offset:2048
	ds_read_b128 v[172:175], v176
	ds_read_b128 v[176:179], v176 offset:2048
	ds_read_b128 v[180:183], v214 offset:32768
	ds_read_b128 v[184:187], v214 offset:34816
	ds_read_b128 v[188:191], v215 offset:32768
	ds_read_b128 v[192:195], v215 offset:34816
	ds_read_b128 v[196:199], v214 offset:36864
	ds_read_b128 v[216:219], v214 offset:38912
	ds_read_b128 v[220:223], v215 offset:36864
	ds_read_b128 v[224:227], v215 offset:38912
	s_waitcnt vmcnt(8)
	s_waitcnt lgkmcnt(0)
	s_barrier
	s_waitcnt lgkmcnt(0)
	v_mfma_f32_16x16x32_bf16 v[160:163], v[116:119], v[180:183], v[160:163]
	v_mfma_f32_16x16x32_bf16 v[152:155], v[120:123], v[180:183], v[152:155]
	v_mfma_f32_16x16x32_bf16 v[132:135], v[116:119], v[184:187], v[132:135]
	v_mfma_f32_16x16x32_bf16 v[124:127], v[120:123], v[184:187], v[124:127]
	v_mfma_f32_16x16x32_bf16 v[108:111], v[116:119], v[196:199], v[108:111]
	v_mfma_f32_16x16x32_bf16 v[100:103], v[120:123], v[196:199], v[100:103]
	v_mfma_f32_16x16x32_bf16 v[92:95], v[116:119], v[216:219], v[92:95]
	v_mfma_f32_16x16x32_bf16 v[84:87], v[120:123], v[216:219], v[84:87]
	v_mfma_f32_16x16x32_bf16 v[160:163], v[140:143], v[188:191], v[160:163]
	v_mfma_f32_16x16x32_bf16 v[152:155], v[144:147], v[188:191], v[152:155]
	v_mfma_f32_16x16x32_bf16 v[132:135], v[140:143], v[192:195], v[132:135]
	v_mfma_f32_16x16x32_bf16 v[124:127], v[144:147], v[192:195], v[124:127]
	v_mfma_f32_16x16x32_bf16 v[108:111], v[140:143], v[220:223], v[108:111]
	v_mfma_f32_16x16x32_bf16 v[100:103], v[144:147], v[220:223], v[100:103]
	v_mfma_f32_16x16x32_bf16 v[92:95], v[140:143], v[224:227], v[92:95]
	v_mfma_f32_16x16x32_bf16 v[84:87], v[144:147], v[224:227], v[84:87]
	v_mfma_f32_16x16x32_bf16 v[156:159], v[164:167], v[180:183], v[156:159]
	v_mfma_f32_16x16x32_bf16 v[148:151], v[168:171], v[180:183], v[148:151]
	v_mfma_f32_16x16x32_bf16 v[136:139], v[164:167], v[184:187], v[136:139]
	v_mfma_f32_16x16x32_bf16 v[128:131], v[168:171], v[184:187], v[128:131]
	v_mfma_f32_16x16x32_bf16 v[112:115], v[164:167], v[196:199], v[112:115]
	v_mfma_f32_16x16x32_bf16 v[104:107], v[168:171], v[196:199], v[104:107]
	v_mfma_f32_16x16x32_bf16 v[96:99], v[164:167], v[216:219], v[96:99]
	v_mfma_f32_16x16x32_bf16 v[88:91], v[168:171], v[216:219], v[88:91]
	v_mfma_f32_16x16x32_bf16 v[156:159], v[172:175], v[188:191], v[156:159]
	v_mfma_f32_16x16x32_bf16 v[148:151], v[176:179], v[188:191], v[148:151]
	v_mfma_f32_16x16x32_bf16 v[136:139], v[172:175], v[192:195], v[136:139]
	v_mfma_f32_16x16x32_bf16 v[128:131], v[176:179], v[192:195], v[128:131]
	v_mfma_f32_16x16x32_bf16 v[112:115], v[172:175], v[220:223], v[112:115]
	v_mfma_f32_16x16x32_bf16 v[104:107], v[176:179], v[220:223], v[104:107]
	v_mfma_f32_16x16x32_bf16 v[96:99], v[172:175], v[224:227], v[96:99]
	v_mfma_f32_16x16x32_bf16 v[88:91], v[176:179], v[224:227], v[88:91]
	s_barrier
	s_mov_b32 m0, s41
	s_nop 0
	buffer_load_dwordx4 v205, s[8:11], s82 offen lds
	s_mov_b32 m0, s42
	s_nop 0
	buffer_load_dwordx4 v207, s[8:11], s82 offen lds
	s_add_i32 s82, s82, s29
	s_mov_b32 m0, s45
	s_nop 0
	buffer_load_dwordx4 v205, s[8:11], s82 offen lds
	s_mov_b32 m0, s46
	s_nop 0
	buffer_load_dwordx4 v207, s[8:11], s82 offen lds
	s_mov_b32 m0, s43
	s_nop 0
	buffer_load_dwordx4 v204, s[48:51], s81 offen lds
	s_mov_b32 m0, s44
	s_nop 0
	buffer_load_dwordx4 v206, s[48:51], s81 offen lds
	ds_read_b128 v[180:183], v214 offset:49152
	ds_read_b128 v[184:187], v214 offset:51200
	ds_read_b128 v[188:191], v215 offset:49152
	ds_read_b128 v[192:195], v215 offset:51200
	ds_read_b128 v[196:199], v214 offset:53248
	ds_read_b128 v[216:219], v214 offset:55296
	ds_read_b128 v[220:223], v215 offset:53248
	ds_read_b128 v[224:227], v215 offset:55296
	s_waitcnt vmcnt(8)
	s_waitcnt lgkmcnt(0)
	s_barrier
	s_waitcnt lgkmcnt(0)
	v_mfma_f32_16x16x32_bf16 v[76:79], v[116:119], v[180:183], v[76:79]
	v_mfma_f32_16x16x32_bf16 v[68:71], v[120:123], v[180:183], v[68:71]
	v_mfma_f32_16x16x32_bf16 v[60:63], v[116:119], v[184:187], v[60:63]
	v_mfma_f32_16x16x32_bf16 v[52:55], v[120:123], v[184:187], v[52:55]
	v_mfma_f32_16x16x32_bf16 v[44:47], v[116:119], v[196:199], v[44:47]
	v_mfma_f32_16x16x32_bf16 v[36:39], v[120:123], v[196:199], v[36:39]
	v_mfma_f32_16x16x32_bf16 v[24:27], v[116:119], v[216:219], v[24:27]
	v_mfma_f32_16x16x32_bf16 v[20:23], v[120:123], v[216:219], v[20:23]
	v_mfma_f32_16x16x32_bf16 v[76:79], v[140:143], v[188:191], v[76:79]
	v_mfma_f32_16x16x32_bf16 v[68:71], v[144:147], v[188:191], v[68:71]
	v_mfma_f32_16x16x32_bf16 v[60:63], v[140:143], v[192:195], v[60:63]
	v_mfma_f32_16x16x32_bf16 v[52:55], v[144:147], v[192:195], v[52:55]
	v_mfma_f32_16x16x32_bf16 v[44:47], v[140:143], v[220:223], v[44:47]
	v_mfma_f32_16x16x32_bf16 v[36:39], v[144:147], v[220:223], v[36:39]
	v_mfma_f32_16x16x32_bf16 v[24:27], v[140:143], v[224:227], v[24:27]
	v_mfma_f32_16x16x32_bf16 v[20:23], v[144:147], v[224:227], v[20:23]
	v_mfma_f32_16x16x32_bf16 v[80:83], v[164:167], v[180:183], v[80:83]
	v_mfma_f32_16x16x32_bf16 v[72:75], v[168:171], v[180:183], v[72:75]
	v_mfma_f32_16x16x32_bf16 v[64:67], v[164:167], v[184:187], v[64:67]
	v_mfma_f32_16x16x32_bf16 v[56:59], v[168:171], v[184:187], v[56:59]
	v_mfma_f32_16x16x32_bf16 v[48:51], v[164:167], v[196:199], v[48:51]
	v_mfma_f32_16x16x32_bf16 v[40:43], v[168:171], v[196:199], v[40:43]
	v_mfma_f32_16x16x32_bf16 v[28:31], v[164:167], v[216:219], v[28:31]
	v_mfma_f32_16x16x32_bf16 v[32:35], v[168:171], v[216:219], v[32:35]
	v_mfma_f32_16x16x32_bf16 v[80:83], v[172:175], v[188:191], v[80:83]
	v_mfma_f32_16x16x32_bf16 v[72:75], v[176:179], v[188:191], v[72:75]
	v_mfma_f32_16x16x32_bf16 v[64:67], v[172:175], v[192:195], v[64:67]
	v_mfma_f32_16x16x32_bf16 v[56:59], v[176:179], v[192:195], v[56:59]
	v_mfma_f32_16x16x32_bf16 v[48:51], v[172:175], v[220:223], v[48:51]
	v_mfma_f32_16x16x32_bf16 v[40:43], v[176:179], v[220:223], v[40:43]
	v_mfma_f32_16x16x32_bf16 v[28:31], v[172:175], v[224:227], v[28:31]
	v_mfma_f32_16x16x32_bf16 v[32:35], v[176:179], v[224:227], v[32:35]
	s_barrier
